# GEMM main loops: loop-invariant LDS-DMA destination bases precomputed into SGPRs in the preheader (8 fewer SALU per iteration)
# baseline (speedup 1.0000x reference)
; template <class Epi>
; __device__ __forceinline__ void gemm_phase(LAS unsigned char* lds, const Gemm g, const StaticOrder& S, const Epi& E) {
;     ...
;     f32x4 acc[2][2][4][2];
; #pragma unroll
;     for (int a = 0; a < 2; ++a)
; #pragma unroll
;         for (int b = 0; b < 2; ++b)
; #pragma unroll
;             for (int m = 0; m < 4; ++m)
; #pragma unroll
;                 for (int n = 0; n < 2; ++n) acc[a][b][m][n] = (f32x4){0.f, 0.f, 0.f, 0.f};
;     ...
; #pragma unroll
;         for (int a = 0; a < 2; ++a)
; #pragma unroll
;             for (int b = 0; b < 2; ++b)
; #pragma unroll
;                 for (int m = 0; m < 4; ++m)
; #pragma unroll
;                     for (int n = 0; n < 2; ++n) acc[a][b][m][n] = (f32x4){0.f, 0.f, 0.f, 0.f};
;         cur = nxt; cA = nA; cB = nB; ++ui;
.LBB0_117:
	v_mov_b32_e32 v127, 0
	s_andn2_b64 vcc, exec, s[6:7]
	v_mov_b32_e32 v126, v127
	v_mov_b32_e32 v125, v127
	v_mov_b32_e32 v124, v127
	v_mov_b32_e32 v123, v127
	v_mov_b32_e32 v122, v127
	v_mov_b32_e32 v121, v127
	v_mov_b32_e32 v120, v127
	v_mov_b32_e32 v111, v127
	v_mov_b32_e32 v110, v127
	v_mov_b32_e32 v109, v127
	v_mov_b32_e32 v108, v127
	v_mov_b32_e32 v107, v127
	v_mov_b32_e32 v106, v127
	v_mov_b32_e32 v105, v127
	v_mov_b32_e32 v104, v127
	v_mov_b32_e32 v95, v127
	v_mov_b32_e32 v94, v127
	v_mov_b32_e32 v93, v127
	v_mov_b32_e32 v92, v127
	v_mov_b32_e32 v91, v127
	v_mov_b32_e32 v90, v127
	v_mov_b32_e32 v89, v127
	v_mov_b32_e32 v88, v127
	v_mov_b32_e32 v79, v127
	v_mov_b32_e32 v78, v127
	v_mov_b32_e32 v77, v127
	v_mov_b32_e32 v76, v127
	v_mov_b32_e32 v75, v127
	v_mov_b32_e32 v74, v127
	v_mov_b32_e32 v73, v127
	v_mov_b32_e32 v72, v127
	v_mov_b32_e32 v119, v127
	v_mov_b32_e32 v118, v127
	v_mov_b32_e32 v117, v127
	v_mov_b32_e32 v116, v127
	v_mov_b32_e32 v115, v127
	v_mov_b32_e32 v114, v127
	v_mov_b32_e32 v113, v127
	v_mov_b32_e32 v112, v127
	v_mov_b32_e32 v103, v127
	v_mov_b32_e32 v102, v127
	v_mov_b32_e32 v101, v127
	v_mov_b32_e32 v100, v127
	v_mov_b32_e32 v99, v127
	v_mov_b32_e32 v98, v127
	v_mov_b32_e32 v97, v127
	v_mov_b32_e32 v96, v127
	v_mov_b32_e32 v87, v127
	v_mov_b32_e32 v86, v127
	v_mov_b32_e32 v85, v127
	v_mov_b32_e32 v84, v127
	v_mov_b32_e32 v83, v127
	v_mov_b32_e32 v82, v127
	v_mov_b32_e32 v81, v127
	v_mov_b32_e32 v80, v127
	v_mov_b32_e32 v71, v127
	v_mov_b32_e32 v70, v127
	v_mov_b32_e32 v69, v127
	v_mov_b32_e32 v68, v127
	v_mov_b32_e32 v67, v127
	v_mov_b32_e32 v66, v127
	v_mov_b32_e32 v65, v127
	v_mov_b32_e32 v64, v127
	v_mov_b32_e32 v63, v127
	v_mov_b32_e32 v62, v127
	v_mov_b32_e32 v61, v127
	v_mov_b32_e32 v60, v127
	v_mov_b32_e32 v59, v127
	v_mov_b32_e32 v58, v127
	v_mov_b32_e32 v57, v127
	v_mov_b32_e32 v56, v127
	v_mov_b32_e32 v47, v127
	v_mov_b32_e32 v46, v127
	v_mov_b32_e32 v45, v127
	v_mov_b32_e32 v44, v127
	v_mov_b32_e32 v43, v127
	v_mov_b32_e32 v42, v127
	v_mov_b32_e32 v41, v127
	v_mov_b32_e32 v40, v127
	v_mov_b32_e32 v31, v127
	v_mov_b32_e32 v30, v127
	v_mov_b32_e32 v29, v127
	v_mov_b32_e32 v28, v127
	v_mov_b32_e32 v27, v127
	v_mov_b32_e32 v26, v127
	v_mov_b32_e32 v25, v127
	v_mov_b32_e32 v24, v127
	v_mov_b32_e32 v15, v127
	v_mov_b32_e32 v14, v127
	v_mov_b32_e32 v13, v127
	v_mov_b32_e32 v12, v127
	v_mov_b32_e32 v11, v127
	v_mov_b32_e32 v10, v127
	v_mov_b32_e32 v9, v127
	v_mov_b32_e32 v8, v127
	v_mov_b32_e32 v55, v127
	v_mov_b32_e32 v54, v127
	v_mov_b32_e32 v53, v127
	v_mov_b32_e32 v52, v127
	v_mov_b32_e32 v51, v127
	v_mov_b32_e32 v50, v127
	v_mov_b32_e32 v49, v127
	v_mov_b32_e32 v48, v127
	v_mov_b32_e32 v39, v127
	v_mov_b32_e32 v38, v127
	v_mov_b32_e32 v37, v127
	v_mov_b32_e32 v36, v127
	v_mov_b32_e32 v35, v127
	v_mov_b32_e32 v34, v127
	v_mov_b32_e32 v33, v127
	v_mov_b32_e32 v32, v127
	v_mov_b32_e32 v23, v127
	v_mov_b32_e32 v22, v127
	v_mov_b32_e32 v21, v127
	v_mov_b32_e32 v20, v127
	v_mov_b32_e32 v19, v127
	v_mov_b32_e32 v18, v127
	v_mov_b32_e32 v17, v127
	v_mov_b32_e32 v16, v127
	v_mov_b32_e32 v7, v127
	v_mov_b32_e32 v6, v127
	v_mov_b32_e32 v5, v127
	v_mov_b32_e32 v4, v127
	v_mov_b32_e32 v3, v127
	v_mov_b32_e32 v2, v127
	s_waitcnt lgkmcnt(0)
	v_mov_b32_e32 v1, v127
	v_mov_b32_e32 v0, v127
	s_cbranch_vccnz .LBB0_120
	s_add_u32 s39, s14, 0x100
	s_addc_u32 s40, s15, 0
	s_add_u32 s14, s16, 0x80
	v_mov_b32_e32 v0, 0
	s_addc_u32 s15, s17, 0
	s_mov_b32 s16, 0
	v_mov_b32_e32 v1, v0
	v_mov_b32_e32 v2, v0
	v_mov_b32_e32 v3, v0
	v_mov_b32_e32 v4, v0
	v_mov_b32_e32 v5, v0
	v_mov_b32_e32 v6, v0
	v_mov_b32_e32 v7, v0
	v_mov_b32_e32 v16, v0
	v_mov_b32_e32 v17, v0
	v_mov_b32_e32 v18, v0
	v_mov_b32_e32 v19, v0
	v_mov_b32_e32 v20, v0
	v_mov_b32_e32 v21, v0
	v_mov_b32_e32 v22, v0
	v_mov_b32_e32 v23, v0
	v_mov_b32_e32 v32, v0
	v_mov_b32_e32 v33, v0
	v_mov_b32_e32 v34, v0
	v_mov_b32_e32 v35, v0
	v_mov_b32_e32 v36, v0
	v_mov_b32_e32 v37, v0
	v_mov_b32_e32 v38, v0
	v_mov_b32_e32 v39, v0
	v_mov_b32_e32 v48, v0
	v_mov_b32_e32 v49, v0
	v_mov_b32_e32 v50, v0
	v_mov_b32_e32 v51, v0
	v_mov_b32_e32 v52, v0
	v_mov_b32_e32 v53, v0
	v_mov_b32_e32 v54, v0
	v_mov_b32_e32 v55, v0
	v_mov_b32_e32 v8, v0
	v_mov_b32_e32 v9, v0
	v_mov_b32_e32 v10, v0
	v_mov_b32_e32 v11, v0
	v_mov_b32_e32 v12, v0
	v_mov_b32_e32 v13, v0
	v_mov_b32_e32 v14, v0
	v_mov_b32_e32 v15, v0
	v_mov_b32_e32 v24, v0
	v_mov_b32_e32 v25, v0
	v_mov_b32_e32 v26, v0
	v_mov_b32_e32 v27, v0
	v_mov_b32_e32 v28, v0
	v_mov_b32_e32 v29, v0
	v_mov_b32_e32 v30, v0
	v_mov_b32_e32 v31, v0
	v_mov_b32_e32 v40, v0
	v_mov_b32_e32 v41, v0
	v_mov_b32_e32 v42, v0
	v_mov_b32_e32 v43, v0
	v_mov_b32_e32 v44, v0
	v_mov_b32_e32 v45, v0
	v_mov_b32_e32 v46, v0
	v_mov_b32_e32 v47, v0
	v_mov_b32_e32 v56, v0
	v_mov_b32_e32 v57, v0
	v_mov_b32_e32 v58, v0
	v_mov_b32_e32 v59, v0
	v_mov_b32_e32 v60, v0
	v_mov_b32_e32 v61, v0
	v_mov_b32_e32 v62, v0
	v_mov_b32_e32 v63, v0
	v_mov_b32_e32 v64, v0
	v_mov_b32_e32 v65, v0
	v_mov_b32_e32 v66, v0
	v_mov_b32_e32 v67, v0
	v_mov_b32_e32 v68, v0
	v_mov_b32_e32 v69, v0
	v_mov_b32_e32 v70, v0
	v_mov_b32_e32 v71, v0
	v_mov_b32_e32 v80, v0
	v_mov_b32_e32 v81, v0
	v_mov_b32_e32 v82, v0
	v_mov_b32_e32 v83, v0
	v_mov_b32_e32 v84, v0
	v_mov_b32_e32 v85, v0
	v_mov_b32_e32 v86, v0
	v_mov_b32_e32 v87, v0
	v_mov_b32_e32 v96, v0
	v_mov_b32_e32 v97, v0
	v_mov_b32_e32 v98, v0
	v_mov_b32_e32 v99, v0
	v_mov_b32_e32 v100, v0
	v_mov_b32_e32 v101, v0
	v_mov_b32_e32 v102, v0
	v_mov_b32_e32 v103, v0
	v_mov_b32_e32 v112, v0
	v_mov_b32_e32 v113, v0
	v_mov_b32_e32 v114, v0
	v_mov_b32_e32 v115, v0
	v_mov_b32_e32 v116, v0
	v_mov_b32_e32 v117, v0
	v_mov_b32_e32 v118, v0
	v_mov_b32_e32 v119, v0
	v_mov_b32_e32 v72, v0
	v_mov_b32_e32 v73, v0
	v_mov_b32_e32 v74, v0
	v_mov_b32_e32 v75, v0
	v_mov_b32_e32 v76, v0
	v_mov_b32_e32 v77, v0
	v_mov_b32_e32 v78, v0
	v_mov_b32_e32 v79, v0
	v_mov_b32_e32 v88, v0
	v_mov_b32_e32 v89, v0
	v_mov_b32_e32 v90, v0
	v_mov_b32_e32 v91, v0
	v_mov_b32_e32 v92, v0
	v_mov_b32_e32 v93, v0
	v_mov_b32_e32 v94, v0
	v_mov_b32_e32 v95, v0
	v_mov_b32_e32 v104, v0
	v_mov_b32_e32 v105, v0
	v_mov_b32_e32 v106, v0
	v_mov_b32_e32 v107, v0
	v_mov_b32_e32 v108, v0
	v_mov_b32_e32 v109, v0
	v_mov_b32_e32 v110, v0
	v_mov_b32_e32 v111, v0
	v_mov_b32_e32 v120, v0
	v_mov_b32_e32 v121, v0
	v_mov_b32_e32 v122, v0
	v_mov_b32_e32 v123, v0
	v_mov_b32_e32 v124, v0
	v_mov_b32_e32 v125, v0
	v_mov_b32_e32 v126, v0
	v_mov_b32_e32 v127, v0
	s_mov_b64 s[44:45], 0x80
	v_add_u32_e32 v224, 0x10000, v245
	v_add_u32_e32 v225, 0x14000, v245
	v_add_u32_e32 v226, 0x18000, v245
	v_add_u32_e32 v227, 0x1c000, v245
	s_add_i32 s86, s23, 0x10000
	s_add_i32 s87, s23, 0x14000
	s_add_i32 s88, s23, 0x18000
	s_add_i32 s89, s23, 0x1c000
; #define PG8_STAGE(bufoff, gbase, voff) do { _Pragma("unroll") for (int _i = 0; _i < 2; ++_i) \
;         __builtin_amdgcn_global_load_lds((const unsigned*)((const char*)(gbase) + (voff)[_i]), (LAS unsigned*)(lds + (bufoff) + ldsw + _i * 8192), 16, 0, 0); } while (0)
; #define PG8_LDA(dst, b, h) do { _Pragma("unroll") for (int m = 0; m < 4; ++m) _Pragma("unroll") for (int k = 0; k < 2; ++k) dst[m][k] = *(const LAS bf16x8*)(lds + PG8_SA(b, h) + aoff + m * 2048 + k * 1024); } while (0)
; #define PG8_LDB(dst, b, h) do { _Pragma("unroll") for (int n = 0; n < 2; ++n) _Pragma("unroll") for (int k = 0; k < 2; ++k) dst[n][k] = *(const LAS bf16x8*)(lds + PG8_SB(b, h) + boff + n * 2048 + k * 1024); } while (0)
; #define PG8_WAIT_V(n) asm volatile("s_waitcnt vmcnt(" #n ")" ::: "memory")
; #define PG8_WAIT_L(n) asm volatile("s_waitcnt lgkmcnt(" #n ")" ::: "memory")
; #define PG8_BAR __builtin_amdgcn_s_barrier()
; #define PG8_SCHED __builtin_amdgcn_sched_barrier(0)
; template <class Epi>
; __device__ __forceinline__ void gemm_phase(LAS unsigned char* lds, const Gemm g, const StaticOrder& S, const Epi& E) {
;     ...
;         const bool has_next = S.next(ui + 1, nxt);
;         const char* nA = has_next ? (const char*)g.A + (size_t)nxt.pm * tstep : cA; const char* nB = has_next ? (const char*)g.Bt + (size_t)nxt.pn * tstep : cB;
;         for (int t = 0; t < nt; t += 2) {
;             const bool last = (t == nt - 2);
;             const char* a1 = cA + (size_t)(t + 1) * kstep;
;             const char* a2 = last ? nA : cA + (size_t)(t + 2) * kstep; const char* b2 = last ? nB : cB + (size_t)(t + 2) * kstep;
;             const char* a3 = a2 + kstep; const char* b3 = b2 + kstep;
;             PG8_LDB(B0, 0, 0); PG8_SCHED; PG8_LDA(At, 0, 0); PG8_STAGE(PG8_SA(1, 1), a1 + hstep, voffA);
;             PG8_WAIT_L(8); PG8_BAR; PG8_WAIT_L(0); PG8_MMA(0, 0, At, B0); PG8_BAR; PG8_SCHED;
;             PG8_LDB(B1, 0, 1); PG8_STAGE(PG8_SB(0, 0), b2, voffB);
;             PG8_BAR; PG8_WAIT_L(0); PG8_MMA(0, 1, At, B1); PG8_BAR;
;             PG8_LDA(At, 0, 1); PG8_STAGE(PG8_SA(0, 0), a2, voffA);
;             PG8_BAR; PG8_WAIT_L(0); PG8_MMA(1, 0, At, B0); PG8_BAR; PG8_SCHED;
;             PG8_STAGE(PG8_SB(0, 1), b2 + hstep, voffB);
;             PG8_WAIT_V(6); PG8_BAR; PG8_MMA(1, 1, At, B1); PG8_BAR;
.LBB0_119:
	s_add_i32 s41, s16, 2
	s_add_u32 s18, s14, 0x80
	s_addc_u32 s17, s15, 0
	ds_read_b128 v[128:131], v224
	ds_read_b128 v[132:135], v224 offset:1024
	ds_read_b128 v[136:139], v224 offset:2048
	ds_read_b128 v[140:143], v224 offset:3072
	s_cmp_eq_u32 s31, s16
	s_cselect_b32 s16, s10, s18
	s_cselect_b32 s17, s11, s17
	s_cselect_b32 s19, s13, s40
	s_cselect_b32 s18, s12, s39
	s_add_i32 m0, s24, 0xc000
	ds_read_b128 v[144:147], v247
	ds_read_b128 v[148:151], v247 offset:1024
	ds_read_b128 v[152:155], v247 offset:2048
	ds_read_b128 v[156:159], v247 offset:3072
	ds_read_b128 v[160:163], v247 offset:4096
	ds_read_b128 v[164:167], v247 offset:5120
	ds_read_b128 v[168:171], v247 offset:6144
	global_load_lds_dwordx4 v210, s[14:15]
	s_add_i32 m0, s24, 0xe000
	ds_read_b128 v[172:175], v247 offset:7168
	global_load_lds_dwordx4 v208, s[14:15]
	s_waitcnt lgkmcnt(8)
	s_barrier
	s_waitcnt lgkmcnt(0)
	v_mfma_f32_16x16x32_bf16 v[124:127], v[128:131], v[144:147], v[124:127]
	v_mfma_f32_16x16x32_bf16 v[120:123], v[136:139], v[144:147], v[120:123]
	v_mfma_f32_16x16x32_bf16 v[108:111], v[128:131], v[152:155], v[108:111]
	v_mfma_f32_16x16x32_bf16 v[104:107], v[136:139], v[152:155], v[104:107]
	v_mfma_f32_16x16x32_bf16 v[92:95], v[128:131], v[160:163], v[92:95]
	v_mfma_f32_16x16x32_bf16 v[88:91], v[136:139], v[160:163], v[88:91]
	v_mfma_f32_16x16x32_bf16 v[76:79], v[128:131], v[168:171], v[76:79]
	v_mfma_f32_16x16x32_bf16 v[72:75], v[136:139], v[168:171], v[72:75]
	v_mfma_f32_16x16x32_bf16 v[124:127], v[132:135], v[148:151], v[124:127]
	v_mfma_f32_16x16x32_bf16 v[120:123], v[140:143], v[148:151], v[120:123]
	v_mfma_f32_16x16x32_bf16 v[108:111], v[132:135], v[156:159], v[108:111]
	v_mfma_f32_16x16x32_bf16 v[104:107], v[140:143], v[156:159], v[104:107]
	v_mfma_f32_16x16x32_bf16 v[92:95], v[132:135], v[164:167], v[92:95]
	v_mfma_f32_16x16x32_bf16 v[88:91], v[140:143], v[164:167], v[88:91]
	v_mfma_f32_16x16x32_bf16 v[76:79], v[132:135], v[172:175], v[76:79]
	v_mfma_f32_16x16x32_bf16 v[72:75], v[140:143], v[172:175], v[72:75]
	s_barrier
	s_add_u32 s80, s18, 0x80
	s_addc_u32 s81, s19, 0
	s_mov_b32 m0, s86
	ds_read_b128 v[176:179], v225
	ds_read_b128 v[180:183], v225 offset:1024
	ds_read_b128 v[184:187], v225 offset:2048
	global_load_lds_dwordx4 v194, s[18:19]
	s_add_i32 m0, s86, 0x2000
	ds_read_b128 v[188:191], v225 offset:3072
	global_load_lds_dwordx4 v206, s[18:19]
	s_barrier
	s_waitcnt lgkmcnt(0)
	v_mfma_f32_16x16x32_bf16 v[116:119], v[176:179], v[144:147], v[116:119]
	v_mfma_f32_16x16x32_bf16 v[112:115], v[184:187], v[144:147], v[112:115]
	v_mfma_f32_16x16x32_bf16 v[100:103], v[176:179], v[152:155], v[100:103]
	v_mfma_f32_16x16x32_bf16 v[96:99], v[184:187], v[152:155], v[96:99]
	v_mfma_f32_16x16x32_bf16 v[84:87], v[176:179], v[160:163], v[84:87]
	v_mfma_f32_16x16x32_bf16 v[80:83], v[184:187], v[160:163], v[80:83]
	v_mfma_f32_16x16x32_bf16 v[68:71], v[176:179], v[168:171], v[68:71]
	v_mfma_f32_16x16x32_bf16 v[64:67], v[184:187], v[168:171], v[64:67]
	v_mfma_f32_16x16x32_bf16 v[116:119], v[180:183], v[148:151], v[116:119]
	v_mfma_f32_16x16x32_bf16 v[112:115], v[188:191], v[148:151], v[112:115]
	v_mfma_f32_16x16x32_bf16 v[100:103], v[180:183], v[156:159], v[100:103]
	v_mfma_f32_16x16x32_bf16 v[96:99], v[188:191], v[156:159], v[96:99]
	v_mfma_f32_16x16x32_bf16 v[84:87], v[180:183], v[164:167], v[84:87]
	v_mfma_f32_16x16x32_bf16 v[80:83], v[188:191], v[164:167], v[80:83]
	v_mfma_f32_16x16x32_bf16 v[68:71], v[180:183], v[172:175], v[68:71]
	v_mfma_f32_16x16x32_bf16 v[64:67], v[188:191], v[172:175], v[64:67]
	s_mov_b32 m0, s24
	s_add_u32 s82, s16, 0x80
	s_addc_u32 s83, s17, 0
	s_barrier
	ds_read_b128 v[144:147], v247 offset:16384
	ds_read_b128 v[148:151], v247 offset:17408
	ds_read_b128 v[152:155], v247 offset:18432
	ds_read_b128 v[156:159], v247 offset:19456
	ds_read_b128 v[160:163], v247 offset:20480
	ds_read_b128 v[164:167], v247 offset:21504
	ds_read_b128 v[168:171], v247 offset:22528
	global_load_lds_dwordx4 v202, s[16:17]
	s_mov_b32 m0, s25
	ds_read_b128 v[172:175], v247 offset:23552
	global_load_lds_dwordx4 v204, s[16:17]
	s_barrier
	s_waitcnt lgkmcnt(0)
	v_mfma_f32_16x16x32_bf16 v[60:63], v[128:131], v[144:147], v[60:63]
	v_mfma_f32_16x16x32_bf16 v[56:59], v[136:139], v[144:147], v[56:59]
	v_mfma_f32_16x16x32_bf16 v[44:47], v[128:131], v[152:155], v[44:47]
	v_mfma_f32_16x16x32_bf16 v[40:43], v[136:139], v[152:155], v[40:43]
	v_mfma_f32_16x16x32_bf16 v[28:31], v[128:131], v[160:163], v[28:31]
	v_mfma_f32_16x16x32_bf16 v[24:27], v[136:139], v[160:163], v[24:27]
	v_mfma_f32_16x16x32_bf16 v[12:15], v[128:131], v[168:171], v[12:15]
	v_mfma_f32_16x16x32_bf16 v[8:11], v[136:139], v[168:171], v[8:11]
	v_mfma_f32_16x16x32_bf16 v[60:63], v[132:135], v[148:151], v[60:63]
	v_mfma_f32_16x16x32_bf16 v[56:59], v[140:143], v[148:151], v[56:59]
	v_mfma_f32_16x16x32_bf16 v[44:47], v[132:135], v[156:159], v[44:47]
	v_mfma_f32_16x16x32_bf16 v[40:43], v[140:143], v[156:159], v[40:43]
	v_mfma_f32_16x16x32_bf16 v[28:31], v[132:135], v[164:167], v[28:31]
	v_mfma_f32_16x16x32_bf16 v[24:27], v[140:143], v[164:167], v[24:27]
	v_mfma_f32_16x16x32_bf16 v[12:15], v[132:135], v[172:175], v[12:15]
	v_mfma_f32_16x16x32_bf16 v[8:11], v[140:143], v[172:175], v[8:11]
	s_barrier
	s_add_u32 s18, s18, s0
	s_addc_u32 s19, s19, s1
	s_add_u32 s84, s18, 0x80
	s_mov_b32 m0, s87
	s_addc_u32 s85, s19, 0
	global_load_lds_dwordx4 v194, s[18:19]
	s_add_i32 m0, s87, 0x2000
	s_nop 0
	global_load_lds_dwordx4 v206, s[18:19]
	s_waitcnt vmcnt(6)
	s_barrier
; #define PG8_STAGE(bufoff, gbase, voff) do { _Pragma("unroll") for (int _i = 0; _i < 2; ++_i) \
;         __builtin_amdgcn_global_load_lds((const unsigned*)((const char*)(gbase) + (voff)[_i]), (LAS unsigned*)(lds + (bufoff) + ldsw + _i * 8192), 16, 0, 0); } while (0)
; #define PG8_LDA(dst, b, h) do { _Pragma("unroll") for (int m = 0; m < 4; ++m) _Pragma("unroll") for (int k = 0; k < 2; ++k) dst[m][k] = *(const LAS bf16x8*)(lds + PG8_SA(b, h) + aoff + m * 2048 + k * 1024); } while (0)
; #define PG8_LDB(dst, b, h) do { _Pragma("unroll") for (int n = 0; n < 2; ++n) _Pragma("unroll") for (int k = 0; k < 2; ++k) dst[n][k] = *(const LAS bf16x8*)(lds + PG8_SB(b, h) + boff + n * 2048 + k * 1024); } while (0)
; #define PG8_MMA(ai, bj, At, Bt) do { __builtin_amdgcn_s_setprio(1); _Pragma("unroll") for (int m = 0; m < 4; ++m) _Pragma("unroll") for (int n = 0; n < 2; ++n) _Pragma("unroll") for (int k = 0; k < 2; ++k) \
;         acc[ai][bj][m][n] = __builtin_amdgcn_mfma_f32_16x16x32_bf16(Bt[n][k], At[m][k], acc[ai][bj][m][n], 0, 0, 0); __builtin_amdgcn_s_setprio(0); } while (0)
; #define PG8_WAIT_V(n) asm volatile("s_waitcnt vmcnt(" #n ")" ::: "memory")
; #define PG8_WAIT_L(n) asm volatile("s_waitcnt lgkmcnt(" #n ")" ::: "memory")
; #define PG8_BAR __builtin_amdgcn_s_barrier()
; #define PG8_SCHED __builtin_amdgcn_sched_barrier(0)
; template <class Epi>
; __device__ __forceinline__ void gemm_phase(LAS unsigned char* lds, const Gemm g, const StaticOrder& S, const Epi& E) {
;     ...
;             PG8_WAIT_V(6); PG8_BAR; PG8_MMA(1, 1, At, B1); PG8_BAR;
;             PG8_LDB(B0, 1, 0); PG8_SCHED; PG8_LDA(At, 1, 0); PG8_STAGE(PG8_SA(0, 1), a2 + hstep, voffA);
;             PG8_WAIT_L(8); PG8_BAR; PG8_WAIT_L(0); PG8_MMA(0, 0, At, B0); PG8_BAR; PG8_SCHED;
;             PG8_LDB(B1, 1, 1); PG8_STAGE(PG8_SB(1, 0), b3, voffB);
	v_mfma_f32_16x16x32_bf16 v[52:55], v[176:179], v[144:147], v[52:55]
	v_mfma_f32_16x16x32_bf16 v[48:51], v[184:187], v[144:147], v[48:51]
	v_mfma_f32_16x16x32_bf16 v[36:39], v[176:179], v[152:155], v[36:39]
	v_mfma_f32_16x16x32_bf16 v[32:35], v[184:187], v[152:155], v[32:35]
	v_mfma_f32_16x16x32_bf16 v[20:23], v[176:179], v[160:163], v[20:23]
	v_mfma_f32_16x16x32_bf16 v[16:19], v[184:187], v[160:163], v[16:19]
	v_mfma_f32_16x16x32_bf16 v[4:7], v[176:179], v[168:171], v[4:7]
	v_mfma_f32_16x16x32_bf16 v[0:3], v[184:187], v[168:171], v[0:3]
	v_mfma_f32_16x16x32_bf16 v[52:55], v[180:183], v[148:151], v[52:55]
	v_mfma_f32_16x16x32_bf16 v[48:51], v[188:191], v[148:151], v[48:51]
	v_mfma_f32_16x16x32_bf16 v[36:39], v[180:183], v[156:159], v[36:39]
	v_mfma_f32_16x16x32_bf16 v[32:35], v[188:191], v[156:159], v[32:35]
	v_mfma_f32_16x16x32_bf16 v[20:23], v[180:183], v[164:167], v[20:23]
	v_mfma_f32_16x16x32_bf16 v[16:19], v[188:191], v[164:167], v[16:19]
	v_mfma_f32_16x16x32_bf16 v[4:7], v[180:183], v[172:175], v[4:7]
	v_mfma_f32_16x16x32_bf16 v[0:3], v[188:191], v[172:175], v[0:3]
	s_barrier
	ds_read_b128 v[128:131], v226
	ds_read_b128 v[132:135], v226 offset:1024
	ds_read_b128 v[136:139], v226 offset:2048
	ds_read_b128 v[140:143], v226 offset:3072
	s_add_u32 s16, s16, s0
	s_addc_u32 s17, s17, s1
	s_mov_b32 m0, s26
	ds_read_b128 v[144:147], v247 offset:32768
	ds_read_b128 v[148:151], v247 offset:33792
	ds_read_b128 v[152:155], v247 offset:34816
	ds_read_b128 v[156:159], v247 offset:35840
	ds_read_b128 v[160:163], v247 offset:36864
	ds_read_b128 v[164:167], v247 offset:37888
	ds_read_b128 v[168:171], v247 offset:38912
	global_load_lds_dwordx4 v202, s[16:17]
	s_mov_b32 m0, s27
	ds_read_b128 v[172:175], v247 offset:39936
	global_load_lds_dwordx4 v204, s[16:17]
	s_waitcnt lgkmcnt(8)
	s_barrier
	s_waitcnt lgkmcnt(0)
	v_mfma_f32_16x16x32_bf16 v[124:127], v[128:131], v[144:147], v[124:127]
	v_mfma_f32_16x16x32_bf16 v[120:123], v[136:139], v[144:147], v[120:123]
	v_mfma_f32_16x16x32_bf16 v[108:111], v[128:131], v[152:155], v[108:111]
	v_mfma_f32_16x16x32_bf16 v[104:107], v[136:139], v[152:155], v[104:107]
	v_mfma_f32_16x16x32_bf16 v[92:95], v[128:131], v[160:163], v[92:95]
	v_mfma_f32_16x16x32_bf16 v[88:91], v[136:139], v[160:163], v[88:91]
	v_mfma_f32_16x16x32_bf16 v[76:79], v[128:131], v[168:171], v[76:79]
	v_mfma_f32_16x16x32_bf16 v[72:75], v[136:139], v[168:171], v[72:75]
	v_mfma_f32_16x16x32_bf16 v[124:127], v[132:135], v[148:151], v[124:127]
	v_mfma_f32_16x16x32_bf16 v[120:123], v[140:143], v[148:151], v[120:123]
	v_mfma_f32_16x16x32_bf16 v[108:111], v[132:135], v[156:159], v[108:111]
	v_mfma_f32_16x16x32_bf16 v[104:107], v[140:143], v[156:159], v[104:107]
	v_mfma_f32_16x16x32_bf16 v[92:95], v[132:135], v[164:167], v[92:95]
	v_mfma_f32_16x16x32_bf16 v[88:91], v[140:143], v[164:167], v[88:91]
	v_mfma_f32_16x16x32_bf16 v[76:79], v[132:135], v[172:175], v[76:79]
	v_mfma_f32_16x16x32_bf16 v[72:75], v[140:143], v[172:175], v[72:75]
	s_barrier
	s_mov_b32 m0, s88
	ds_read_b128 v[176:179], v227
	ds_read_b128 v[180:183], v227 offset:1024
	ds_read_b128 v[184:187], v227 offset:2048
	global_load_lds_dwordx4 v194, s[80:81]
	s_add_i32 m0, s88, 0x2000
	ds_read_b128 v[188:191], v227 offset:3072
	global_load_lds_dwordx4 v206, s[80:81]
	s_barrier
; #define PG8_STAGE(bufoff, gbase, voff) do { _Pragma("unroll") for (int _i = 0; _i < 2; ++_i) \
;         __builtin_amdgcn_global_load_lds((const unsigned*)((const char*)(gbase) + (voff)[_i]), (LAS unsigned*)(lds + (bufoff) + ldsw + _i * 8192), 16, 0, 0); } while (0)
; #define PG8_LDA(dst, b, h) do { _Pragma("unroll") for (int m = 0; m < 4; ++m) _Pragma("unroll") for (int k = 0; k < 2; ++k) dst[m][k] = *(const LAS bf16x8*)(lds + PG8_SA(b, h) + aoff + m * 2048 + k * 1024); } while (0)
; #define PG8_MMA(ai, bj, At, Bt) do { __builtin_amdgcn_s_setprio(1); _Pragma("unroll") for (int m = 0; m < 4; ++m) _Pragma("unroll") for (int n = 0; n < 2; ++n) _Pragma("unroll") for (int k = 0; k < 2; ++k) \
;         acc[ai][bj][m][n] = __builtin_amdgcn_mfma_f32_16x16x32_bf16(Bt[n][k], At[m][k], acc[ai][bj][m][n], 0, 0, 0); __builtin_amdgcn_s_setprio(0); } while (0)
; #define PG8_WAIT_V(n) asm volatile("s_waitcnt vmcnt(" #n ")" ::: "memory")
; #define PG8_WAIT_L(n) asm volatile("s_waitcnt lgkmcnt(" #n ")" ::: "memory")
; #define PG8_BAR __builtin_amdgcn_s_barrier()
; #define PG8_SCHED __builtin_amdgcn_sched_barrier(0)
; template <class Epi>
; __device__ __forceinline__ void gemm_phase(LAS unsigned char* lds, const Gemm g, const StaticOrder& S, const Epi& E) {
;     ...
;             PG8_BAR; PG8_WAIT_L(0); PG8_MMA(0, 1, At, B1); PG8_BAR;
;             PG8_LDA(At, 1, 1); PG8_STAGE(PG8_SA(1, 0), a3, voffA);
;             PG8_BAR; PG8_WAIT_L(0); PG8_MMA(1, 0, At, B0); PG8_BAR; PG8_SCHED;
;             PG8_STAGE(PG8_SB(1, 1), b3 + hstep, voffB);
;             PG8_WAIT_V(6); PG8_BAR; PG8_MMA(1, 1, At, B1); PG8_BAR;
;         }
	s_waitcnt lgkmcnt(0)
	v_mfma_f32_16x16x32_bf16 v[116:119], v[176:179], v[144:147], v[116:119]
	v_mfma_f32_16x16x32_bf16 v[112:115], v[184:187], v[144:147], v[112:115]
	v_mfma_f32_16x16x32_bf16 v[100:103], v[176:179], v[152:155], v[100:103]
	v_mfma_f32_16x16x32_bf16 v[96:99], v[184:187], v[152:155], v[96:99]
	v_mfma_f32_16x16x32_bf16 v[84:87], v[176:179], v[160:163], v[84:87]
	v_mfma_f32_16x16x32_bf16 v[80:83], v[184:187], v[160:163], v[80:83]
	v_mfma_f32_16x16x32_bf16 v[68:71], v[176:179], v[168:171], v[68:71]
	v_mfma_f32_16x16x32_bf16 v[64:67], v[184:187], v[168:171], v[64:67]
	v_mfma_f32_16x16x32_bf16 v[116:119], v[180:183], v[148:151], v[116:119]
	v_mfma_f32_16x16x32_bf16 v[112:115], v[188:191], v[148:151], v[112:115]
	v_mfma_f32_16x16x32_bf16 v[100:103], v[180:183], v[156:159], v[100:103]
	v_mfma_f32_16x16x32_bf16 v[96:99], v[188:191], v[156:159], v[96:99]
	v_mfma_f32_16x16x32_bf16 v[84:87], v[180:183], v[164:167], v[84:87]
	v_mfma_f32_16x16x32_bf16 v[80:83], v[188:191], v[164:167], v[80:83]
	v_mfma_f32_16x16x32_bf16 v[68:71], v[180:183], v[172:175], v[68:71]
	v_mfma_f32_16x16x32_bf16 v[64:67], v[188:191], v[172:175], v[64:67]
	s_mov_b32 m0, s28
	s_barrier
	ds_read_b128 v[144:147], v247 offset:49152
	ds_read_b128 v[148:151], v247 offset:50176
	ds_read_b128 v[152:155], v247 offset:51200
	ds_read_b128 v[156:159], v247 offset:52224
	ds_read_b128 v[160:163], v247 offset:53248
	ds_read_b128 v[164:167], v247 offset:54272
	ds_read_b128 v[168:171], v247 offset:55296
	global_load_lds_dwordx4 v202, s[82:83]
	s_mov_b32 m0, s29
	ds_read_b128 v[172:175], v247 offset:56320
	global_load_lds_dwordx4 v204, s[82:83]
	s_barrier
	s_waitcnt lgkmcnt(0)
	v_mfma_f32_16x16x32_bf16 v[60:63], v[128:131], v[144:147], v[60:63]
	v_mfma_f32_16x16x32_bf16 v[56:59], v[136:139], v[144:147], v[56:59]
	v_mfma_f32_16x16x32_bf16 v[44:47], v[128:131], v[152:155], v[44:47]
	v_mfma_f32_16x16x32_bf16 v[40:43], v[136:139], v[152:155], v[40:43]
	v_mfma_f32_16x16x32_bf16 v[28:31], v[128:131], v[160:163], v[28:31]
	v_mfma_f32_16x16x32_bf16 v[24:27], v[136:139], v[160:163], v[24:27]
	v_mfma_f32_16x16x32_bf16 v[12:15], v[128:131], v[168:171], v[12:15]
	v_mfma_f32_16x16x32_bf16 v[8:11], v[136:139], v[168:171], v[8:11]
	v_mfma_f32_16x16x32_bf16 v[60:63], v[132:135], v[148:151], v[60:63]
	v_mfma_f32_16x16x32_bf16 v[56:59], v[140:143], v[148:151], v[56:59]
	v_mfma_f32_16x16x32_bf16 v[44:47], v[132:135], v[156:159], v[44:47]
	v_mfma_f32_16x16x32_bf16 v[40:43], v[140:143], v[156:159], v[40:43]
	v_mfma_f32_16x16x32_bf16 v[28:31], v[132:135], v[164:167], v[28:31]
	v_mfma_f32_16x16x32_bf16 v[24:27], v[140:143], v[164:167], v[24:27]
	v_mfma_f32_16x16x32_bf16 v[12:15], v[132:135], v[172:175], v[12:15]
	v_mfma_f32_16x16x32_bf16 v[8:11], v[140:143], v[172:175], v[8:11]
	s_barrier
	s_mov_b32 m0, s89
	s_nop 0
	global_load_lds_dwordx4 v194, s[84:85]
	s_add_i32 m0, s89, 0x2000
	s_nop 0
	global_load_lds_dwordx4 v206, s[84:85]
	s_waitcnt vmcnt(6)
	s_barrier
	v_mfma_f32_16x16x32_bf16 v[52:55], v[176:179], v[144:147], v[52:55]
	v_mfma_f32_16x16x32_bf16 v[48:51], v[184:187], v[144:147], v[48:51]
	v_mfma_f32_16x16x32_bf16 v[36:39], v[176:179], v[152:155], v[36:39]
	v_mfma_f32_16x16x32_bf16 v[32:35], v[184:187], v[152:155], v[32:35]
	v_mfma_f32_16x16x32_bf16 v[20:23], v[176:179], v[160:163], v[20:23]
	v_mfma_f32_16x16x32_bf16 v[16:19], v[184:187], v[160:163], v[16:19]
	v_mfma_f32_16x16x32_bf16 v[4:7], v[176:179], v[168:171], v[4:7]
	v_mfma_f32_16x16x32_bf16 v[0:3], v[184:187], v[168:171], v[0:3]
	v_mfma_f32_16x16x32_bf16 v[52:55], v[180:183], v[148:151], v[52:55]
	v_mfma_f32_16x16x32_bf16 v[48:51], v[188:191], v[148:151], v[48:51]
	v_mfma_f32_16x16x32_bf16 v[36:39], v[180:183], v[156:159], v[36:39]
	v_mfma_f32_16x16x32_bf16 v[32:35], v[188:191], v[156:159], v[32:35]
	v_mfma_f32_16x16x32_bf16 v[20:23], v[180:183], v[164:167], v[20:23]
	v_mfma_f32_16x16x32_bf16 v[16:19], v[188:191], v[164:167], v[16:19]
	v_mfma_f32_16x16x32_bf16 v[4:7], v[180:183], v[172:175], v[4:7]
	v_mfma_f32_16x16x32_bf16 v[0:3], v[188:191], v[172:175], v[0:3]
	s_add_u32 s39, s39, 0x100
	s_addc_u32 s40, s40, 0
	s_add_u32 s14, s14, 0x100
	s_addc_u32 s15, s15, 0
	s_cmp_ge_i32 s41, s30
	s_mov_b32 s16, s41
	s_barrier
	s_cbranch_scc0 .LBB0_119

; template <class Epi>
; __device__ __forceinline__ void gemm_phase(LAS unsigned char* lds, const Gemm g, const StaticOrder& S, const Epi& E) {
;     ...
;     f32x4 acc[2][2][4][2];
; #pragma unroll
;     for (int a = 0; a < 2; ++a)
; #pragma unroll
;         for (int b = 0; b < 2; ++b)
; #pragma unroll
;             for (int m = 0; m < 4; ++m)
; #pragma unroll
;                 for (int n = 0; n < 2; ++n) acc[a][b][m][n] = (f32x4){0.f, 0.f, 0.f, 0.f};
;     ...
; #pragma unroll
;         for (int a = 0; a < 2; ++a)
; #pragma unroll
;             for (int b = 0; b < 2; ++b)
; #pragma unroll
;                 for (int m = 0; m < 4; ++m)
; #pragma unroll
;                     for (int n = 0; n < 2; ++n) acc[a][b][m][n] = (f32x4){0.f, 0.f, 0.f, 0.f};
;         cur = nxt; cA = nA; cB = nB; ++ui;
.LBB0_163:
	v_mov_b32_e32 v127, 0
	s_andn2_b64 vcc, exec, s[6:7]
	v_mov_b32_e32 v126, v127
	v_mov_b32_e32 v125, v127
	v_mov_b32_e32 v124, v127
	v_mov_b32_e32 v123, v127
	v_mov_b32_e32 v122, v127
	v_mov_b32_e32 v121, v127
	v_mov_b32_e32 v120, v127
	v_mov_b32_e32 v111, v127
	v_mov_b32_e32 v110, v127
	v_mov_b32_e32 v109, v127
	v_mov_b32_e32 v108, v127
	v_mov_b32_e32 v107, v127
	v_mov_b32_e32 v106, v127
	v_mov_b32_e32 v105, v127
	v_mov_b32_e32 v104, v127
	v_mov_b32_e32 v95, v127
	v_mov_b32_e32 v94, v127
	v_mov_b32_e32 v93, v127
	v_mov_b32_e32 v92, v127
	v_mov_b32_e32 v91, v127
	v_mov_b32_e32 v90, v127
	v_mov_b32_e32 v89, v127
	v_mov_b32_e32 v88, v127
	v_mov_b32_e32 v79, v127
	v_mov_b32_e32 v78, v127
	v_mov_b32_e32 v77, v127
	v_mov_b32_e32 v76, v127
	v_mov_b32_e32 v75, v127
	v_mov_b32_e32 v74, v127
	v_mov_b32_e32 v73, v127
	v_mov_b32_e32 v72, v127
	v_mov_b32_e32 v119, v127
	v_mov_b32_e32 v118, v127
	v_mov_b32_e32 v117, v127
	v_mov_b32_e32 v116, v127
	v_mov_b32_e32 v115, v127
	v_mov_b32_e32 v114, v127
	v_mov_b32_e32 v113, v127
	v_mov_b32_e32 v112, v127
	v_mov_b32_e32 v103, v127
	v_mov_b32_e32 v102, v127
	v_mov_b32_e32 v101, v127
	v_mov_b32_e32 v100, v127
	v_mov_b32_e32 v99, v127
	v_mov_b32_e32 v98, v127
	v_mov_b32_e32 v97, v127
	v_mov_b32_e32 v96, v127
	v_mov_b32_e32 v87, v127
	v_mov_b32_e32 v86, v127
	v_mov_b32_e32 v85, v127
	v_mov_b32_e32 v84, v127
	v_mov_b32_e32 v83, v127
	v_mov_b32_e32 v82, v127
	v_mov_b32_e32 v81, v127
	v_mov_b32_e32 v80, v127
	v_mov_b32_e32 v71, v127
	v_mov_b32_e32 v70, v127
	v_mov_b32_e32 v69, v127
	v_mov_b32_e32 v68, v127
	v_mov_b32_e32 v67, v127
	v_mov_b32_e32 v66, v127
	v_mov_b32_e32 v65, v127
	v_mov_b32_e32 v64, v127
	v_mov_b32_e32 v63, v127
	v_mov_b32_e32 v62, v127
	v_mov_b32_e32 v61, v127
	v_mov_b32_e32 v60, v127
	v_mov_b32_e32 v59, v127
	v_mov_b32_e32 v58, v127
	v_mov_b32_e32 v57, v127
	v_mov_b32_e32 v56, v127
	v_mov_b32_e32 v47, v127
	v_mov_b32_e32 v46, v127
	v_mov_b32_e32 v45, v127
	v_mov_b32_e32 v44, v127
	v_mov_b32_e32 v43, v127
	v_mov_b32_e32 v42, v127
	v_mov_b32_e32 v41, v127
	v_mov_b32_e32 v40, v127
	v_mov_b32_e32 v31, v127
	v_mov_b32_e32 v30, v127
	v_mov_b32_e32 v29, v127
	v_mov_b32_e32 v28, v127
	v_mov_b32_e32 v27, v127
	v_mov_b32_e32 v26, v127
	v_mov_b32_e32 v25, v127
	v_mov_b32_e32 v24, v127
	v_mov_b32_e32 v15, v127
	v_mov_b32_e32 v14, v127
	v_mov_b32_e32 v13, v127
	v_mov_b32_e32 v12, v127
	v_mov_b32_e32 v11, v127
	v_mov_b32_e32 v10, v127
	v_mov_b32_e32 v9, v127
	v_mov_b32_e32 v8, v127
	v_mov_b32_e32 v55, v127
	v_mov_b32_e32 v54, v127
	v_mov_b32_e32 v53, v127
	v_mov_b32_e32 v52, v127
	v_mov_b32_e32 v51, v127
	v_mov_b32_e32 v50, v127
	v_mov_b32_e32 v49, v127
	v_mov_b32_e32 v48, v127
	v_mov_b32_e32 v39, v127
	v_mov_b32_e32 v38, v127
	v_mov_b32_e32 v37, v127
	v_mov_b32_e32 v36, v127
	v_mov_b32_e32 v35, v127
	v_mov_b32_e32 v34, v127
	v_mov_b32_e32 v33, v127
	v_mov_b32_e32 v32, v127
	v_mov_b32_e32 v23, v127
	v_mov_b32_e32 v22, v127
	v_mov_b32_e32 v21, v127
	v_mov_b32_e32 v20, v127
	v_mov_b32_e32 v19, v127
	v_mov_b32_e32 v18, v127
	v_mov_b32_e32 v17, v127
	v_mov_b32_e32 v16, v127
	v_mov_b32_e32 v7, v127
	v_mov_b32_e32 v6, v127
	v_mov_b32_e32 v5, v127
	v_mov_b32_e32 v4, v127
	v_mov_b32_e32 v3, v127
	v_mov_b32_e32 v2, v127
	v_mov_b32_e32 v1, v127
	v_mov_b32_e32 v0, v127
	s_cbranch_vccnz .LBB0_166
	s_add_u32 s42, s18, 0x100
	s_addc_u32 s43, s19, 0
	s_add_u32 s16, s16, 0x80
	v_mov_b32_e32 v0, 0
	s_addc_u32 s17, s17, 0
	s_mov_b32 s18, 0
	v_mov_b32_e32 v1, v0
	v_mov_b32_e32 v2, v0
	v_mov_b32_e32 v3, v0
	v_mov_b32_e32 v4, v0
	v_mov_b32_e32 v5, v0
	v_mov_b32_e32 v6, v0
	v_mov_b32_e32 v7, v0
	v_mov_b32_e32 v16, v0
	v_mov_b32_e32 v17, v0
	v_mov_b32_e32 v18, v0
	v_mov_b32_e32 v19, v0
	v_mov_b32_e32 v20, v0
	v_mov_b32_e32 v21, v0
	v_mov_b32_e32 v22, v0
	v_mov_b32_e32 v23, v0
	v_mov_b32_e32 v32, v0
	v_mov_b32_e32 v33, v0
	v_mov_b32_e32 v34, v0
	v_mov_b32_e32 v35, v0
	v_mov_b32_e32 v36, v0
	v_mov_b32_e32 v37, v0
	v_mov_b32_e32 v38, v0
	v_mov_b32_e32 v39, v0
	v_mov_b32_e32 v48, v0
	v_mov_b32_e32 v49, v0
	v_mov_b32_e32 v50, v0
	v_mov_b32_e32 v51, v0
	v_mov_b32_e32 v52, v0
	v_mov_b32_e32 v53, v0
	v_mov_b32_e32 v54, v0
	v_mov_b32_e32 v55, v0
	v_mov_b32_e32 v8, v0
	v_mov_b32_e32 v9, v0
	v_mov_b32_e32 v10, v0
	v_mov_b32_e32 v11, v0
	v_mov_b32_e32 v12, v0
	v_mov_b32_e32 v13, v0
	v_mov_b32_e32 v14, v0
	v_mov_b32_e32 v15, v0
	v_mov_b32_e32 v24, v0
	v_mov_b32_e32 v25, v0
	v_mov_b32_e32 v26, v0
	v_mov_b32_e32 v27, v0
	v_mov_b32_e32 v28, v0
	v_mov_b32_e32 v29, v0
	v_mov_b32_e32 v30, v0
	v_mov_b32_e32 v31, v0
	v_mov_b32_e32 v40, v0
	v_mov_b32_e32 v41, v0
	v_mov_b32_e32 v42, v0
	v_mov_b32_e32 v43, v0
	v_mov_b32_e32 v44, v0
	v_mov_b32_e32 v45, v0
	v_mov_b32_e32 v46, v0
	v_mov_b32_e32 v47, v0
	v_mov_b32_e32 v56, v0
	v_mov_b32_e32 v57, v0
	v_mov_b32_e32 v58, v0
	v_mov_b32_e32 v59, v0
	v_mov_b32_e32 v60, v0
	v_mov_b32_e32 v61, v0
	v_mov_b32_e32 v62, v0
	v_mov_b32_e32 v63, v0
	v_mov_b32_e32 v64, v0
	v_mov_b32_e32 v65, v0
	v_mov_b32_e32 v66, v0
	v_mov_b32_e32 v67, v0
	v_mov_b32_e32 v68, v0
	v_mov_b32_e32 v69, v0
	v_mov_b32_e32 v70, v0
	v_mov_b32_e32 v71, v0
	v_mov_b32_e32 v80, v0
	v_mov_b32_e32 v81, v0
	v_mov_b32_e32 v82, v0
	v_mov_b32_e32 v83, v0
	v_mov_b32_e32 v84, v0
	v_mov_b32_e32 v85, v0
	v_mov_b32_e32 v86, v0
	v_mov_b32_e32 v87, v0
	v_mov_b32_e32 v96, v0
	v_mov_b32_e32 v97, v0
	v_mov_b32_e32 v98, v0
	v_mov_b32_e32 v99, v0
	v_mov_b32_e32 v100, v0
	v_mov_b32_e32 v101, v0
	v_mov_b32_e32 v102, v0
	v_mov_b32_e32 v103, v0
	v_mov_b32_e32 v112, v0
	v_mov_b32_e32 v113, v0
	v_mov_b32_e32 v114, v0
	v_mov_b32_e32 v115, v0
	v_mov_b32_e32 v116, v0
	v_mov_b32_e32 v117, v0
	v_mov_b32_e32 v118, v0
	v_mov_b32_e32 v119, v0
	v_mov_b32_e32 v72, v0
	v_mov_b32_e32 v73, v0
	v_mov_b32_e32 v74, v0
	v_mov_b32_e32 v75, v0
	v_mov_b32_e32 v76, v0
	v_mov_b32_e32 v77, v0
	v_mov_b32_e32 v78, v0
	v_mov_b32_e32 v79, v0
	v_mov_b32_e32 v88, v0
	v_mov_b32_e32 v89, v0
	v_mov_b32_e32 v90, v0
	v_mov_b32_e32 v91, v0
	v_mov_b32_e32 v92, v0
	v_mov_b32_e32 v93, v0
	v_mov_b32_e32 v94, v0
	v_mov_b32_e32 v95, v0
	v_mov_b32_e32 v104, v0
	v_mov_b32_e32 v105, v0
	v_mov_b32_e32 v106, v0
	v_mov_b32_e32 v107, v0
	v_mov_b32_e32 v108, v0
	v_mov_b32_e32 v109, v0
	v_mov_b32_e32 v110, v0
	v_mov_b32_e32 v111, v0
	v_mov_b32_e32 v120, v0
	v_mov_b32_e32 v121, v0
	v_mov_b32_e32 v122, v0
	v_mov_b32_e32 v123, v0
	v_mov_b32_e32 v124, v0
	v_mov_b32_e32 v125, v0
	v_mov_b32_e32 v126, v0
	v_mov_b32_e32 v127, v0
	s_mov_b64 s[48:49], 0x80
	v_add_u32_e32 v224, 0x10000, v146
	v_add_u32_e32 v225, 0x14000, v146
	v_add_u32_e32 v226, 0x18000, v146
	v_add_u32_e32 v227, 0x1c000, v146
	s_add_i32 s86, s26, 0x10000
	s_add_i32 s87, s26, 0x14000
	s_add_i32 s88, s26, 0x18000
	s_add_i32 s89, s26, 0x1c000
; #define PG8_STAGE(bufoff, gbase, voff) do { _Pragma("unroll") for (int _i = 0; _i < 2; ++_i) \
;         __builtin_amdgcn_global_load_lds((const unsigned*)((const char*)(gbase) + (voff)[_i]), (LAS unsigned*)(lds + (bufoff) + ldsw + _i * 8192), 16, 0, 0); } while (0)
; #define PG8_LDA(dst, b, h) do { _Pragma("unroll") for (int m = 0; m < 4; ++m) _Pragma("unroll") for (int k = 0; k < 2; ++k) dst[m][k] = *(const LAS bf16x8*)(lds + PG8_SA(b, h) + aoff + m * 2048 + k * 1024); } while (0)
; #define PG8_LDB(dst, b, h) do { _Pragma("unroll") for (int n = 0; n < 2; ++n) _Pragma("unroll") for (int k = 0; k < 2; ++k) dst[n][k] = *(const LAS bf16x8*)(lds + PG8_SB(b, h) + boff + n * 2048 + k * 1024); } while (0)
; #define PG8_WAIT_V(n) asm volatile("s_waitcnt vmcnt(" #n ")" ::: "memory")
; #define PG8_WAIT_L(n) asm volatile("s_waitcnt lgkmcnt(" #n ")" ::: "memory")
; #define PG8_BAR __builtin_amdgcn_s_barrier()
; #define PG8_SCHED __builtin_amdgcn_sched_barrier(0)
; template <class Epi>
; __device__ __forceinline__ void gemm_phase(LAS unsigned char* lds, const Gemm g, const StaticOrder& S, const Epi& E) {
;     ...
;         const bool has_next = S.next(ui + 1, nxt);
;         const char* nA = has_next ? (const char*)g.A + (size_t)nxt.pm * tstep : cA; const char* nB = has_next ? (const char*)g.Bt + (size_t)nxt.pn * tstep : cB;
;         for (int t = 0; t < nt; t += 2) {
;             const bool last = (t == nt - 2);
;             const char* a1 = cA + (size_t)(t + 1) * kstep;
;             const char* a2 = last ? nA : cA + (size_t)(t + 2) * kstep; const char* b2 = last ? nB : cB + (size_t)(t + 2) * kstep;
;             const char* a3 = a2 + kstep; const char* b3 = b2 + kstep;
;             PG8_LDB(B0, 0, 0); PG8_SCHED; PG8_LDA(At, 0, 0); PG8_STAGE(PG8_SA(1, 1), a1 + hstep, voffA);
;             PG8_WAIT_L(8); PG8_BAR; PG8_WAIT_L(0); PG8_MMA(0, 0, At, B0); PG8_BAR; PG8_SCHED;
;             PG8_LDB(B1, 0, 1); PG8_STAGE(PG8_SB(0, 0), b2, voffB);
;             PG8_BAR; PG8_WAIT_L(0); PG8_MMA(0, 1, At, B1); PG8_BAR;
;             PG8_LDA(At, 0, 1); PG8_STAGE(PG8_SA(0, 0), a2, voffA);
;             PG8_BAR; PG8_WAIT_L(0); PG8_MMA(1, 0, At, B0); PG8_BAR; PG8_SCHED;
;             PG8_STAGE(PG8_SB(0, 1), b2 + hstep, voffB);
;             PG8_WAIT_V(6); PG8_BAR; PG8_MMA(1, 1, At, B1); PG8_BAR;
.LBB0_165:
	s_add_i32 s44, s18, 2
	s_add_u32 s20, s16, 0x80
	s_addc_u32 s19, s17, 0
	ds_read_b128 v[138:141], v224
	ds_read_b128 v[152:155], v224 offset:1024
	ds_read_b128 v[156:159], v224 offset:2048
	ds_read_b128 v[160:163], v224 offset:3072
	s_cmp_eq_u32 s35, s18
	s_cselect_b32 s18, s10, s20
	s_cselect_b32 s19, s11, s19
	s_cselect_b32 s21, s13, s43
	s_cselect_b32 s20, s12, s42
	s_add_i32 m0, s27, 0xc000
	ds_read_b128 v[164:167], v150
	ds_read_b128 v[168:171], v150 offset:1024
	ds_read_b128 v[172:175], v150 offset:2048
	ds_read_b128 v[176:179], v150 offset:3072
	ds_read_b128 v[180:183], v150 offset:4096
	ds_read_b128 v[184:187], v150 offset:5120
	ds_read_b128 v[188:191], v150 offset:6144
	global_load_lds_dwordx4 v136, s[16:17]
	s_add_i32 m0, s27, 0xe000
	ds_read_b128 v[202:205], v150 offset:7168
	global_load_lds_dwordx4 v134, s[16:17]
	s_waitcnt lgkmcnt(8)
	s_barrier
	s_waitcnt lgkmcnt(0)
	v_mfma_f32_16x16x32_bf16 v[124:127], v[138:141], v[164:167], v[124:127]
	v_mfma_f32_16x16x32_bf16 v[120:123], v[156:159], v[164:167], v[120:123]
	v_mfma_f32_16x16x32_bf16 v[108:111], v[138:141], v[172:175], v[108:111]
	v_mfma_f32_16x16x32_bf16 v[104:107], v[156:159], v[172:175], v[104:107]
	v_mfma_f32_16x16x32_bf16 v[92:95], v[138:141], v[180:183], v[92:95]
	v_mfma_f32_16x16x32_bf16 v[88:91], v[156:159], v[180:183], v[88:91]
	v_mfma_f32_16x16x32_bf16 v[76:79], v[138:141], v[188:191], v[76:79]
	v_mfma_f32_16x16x32_bf16 v[72:75], v[156:159], v[188:191], v[72:75]
	v_mfma_f32_16x16x32_bf16 v[124:127], v[152:155], v[168:171], v[124:127]
	v_mfma_f32_16x16x32_bf16 v[120:123], v[160:163], v[168:171], v[120:123]
	v_mfma_f32_16x16x32_bf16 v[108:111], v[152:155], v[176:179], v[108:111]
	v_mfma_f32_16x16x32_bf16 v[104:107], v[160:163], v[176:179], v[104:107]
	v_mfma_f32_16x16x32_bf16 v[92:95], v[152:155], v[184:187], v[92:95]
	v_mfma_f32_16x16x32_bf16 v[88:91], v[160:163], v[184:187], v[88:91]
	v_mfma_f32_16x16x32_bf16 v[76:79], v[152:155], v[202:205], v[76:79]
	v_mfma_f32_16x16x32_bf16 v[72:75], v[160:163], v[202:205], v[72:75]
	s_barrier
	ds_read_b128 v[206:209], v225
	ds_read_b128 v[210:213], v225 offset:1024
	s_add_u32 s80, s20, 0x80
	s_addc_u32 s81, s21, 0
	s_mov_b32 m0, s86
	ds_read_b128 v[218:221], v225 offset:3072
	global_load_lds_dwordx4 v194, s[20:21]
	s_add_i32 m0, s86, 0x2000
	ds_read_b128 v[214:217], v225 offset:2048
	global_load_lds_dwordx4 v132, s[20:21]
	s_barrier
	s_waitcnt lgkmcnt(0)
	v_mfma_f32_16x16x32_bf16 v[116:119], v[206:209], v[164:167], v[116:119]
	v_mfma_f32_16x16x32_bf16 v[112:115], v[214:217], v[164:167], v[112:115]
	v_mfma_f32_16x16x32_bf16 v[100:103], v[206:209], v[172:175], v[100:103]
	v_mfma_f32_16x16x32_bf16 v[96:99], v[214:217], v[172:175], v[96:99]
	v_mfma_f32_16x16x32_bf16 v[84:87], v[206:209], v[180:183], v[84:87]
	v_mfma_f32_16x16x32_bf16 v[80:83], v[214:217], v[180:183], v[80:83]
	v_mfma_f32_16x16x32_bf16 v[68:71], v[206:209], v[188:191], v[68:71]
	v_mfma_f32_16x16x32_bf16 v[64:67], v[214:217], v[188:191], v[64:67]
	v_mfma_f32_16x16x32_bf16 v[116:119], v[210:213], v[168:171], v[116:119]
	v_mfma_f32_16x16x32_bf16 v[112:115], v[218:221], v[168:171], v[112:115]
	v_mfma_f32_16x16x32_bf16 v[100:103], v[210:213], v[176:179], v[100:103]
	v_mfma_f32_16x16x32_bf16 v[96:99], v[218:221], v[176:179], v[96:99]
	v_mfma_f32_16x16x32_bf16 v[84:87], v[210:213], v[184:187], v[84:87]
	v_mfma_f32_16x16x32_bf16 v[80:83], v[218:221], v[184:187], v[80:83]
	v_mfma_f32_16x16x32_bf16 v[68:71], v[210:213], v[202:205], v[68:71]
	v_mfma_f32_16x16x32_bf16 v[64:67], v[218:221], v[202:205], v[64:67]
	s_mov_b32 m0, s27
	s_add_u32 s82, s18, 0x80
	s_addc_u32 s83, s19, 0
	s_barrier
	ds_read_b128 v[164:167], v150 offset:16384
	ds_read_b128 v[168:171], v150 offset:17408
	ds_read_b128 v[172:175], v150 offset:18432
	ds_read_b128 v[176:179], v150 offset:19456
	ds_read_b128 v[180:183], v150 offset:20480
	ds_read_b128 v[184:187], v150 offset:21504
	ds_read_b128 v[188:191], v150 offset:22528
	global_load_lds_dwordx4 v128, s[18:19]
	s_mov_b32 m0, s28
	ds_read_b128 v[202:205], v150 offset:23552
	global_load_lds_dwordx4 v130, s[18:19]
	s_barrier
	s_waitcnt lgkmcnt(0)
	v_mfma_f32_16x16x32_bf16 v[60:63], v[138:141], v[164:167], v[60:63]
	v_mfma_f32_16x16x32_bf16 v[56:59], v[156:159], v[164:167], v[56:59]
	v_mfma_f32_16x16x32_bf16 v[44:47], v[138:141], v[172:175], v[44:47]
	v_mfma_f32_16x16x32_bf16 v[40:43], v[156:159], v[172:175], v[40:43]
	v_mfma_f32_16x16x32_bf16 v[28:31], v[138:141], v[180:183], v[28:31]
	v_mfma_f32_16x16x32_bf16 v[24:27], v[156:159], v[180:183], v[24:27]
	v_mfma_f32_16x16x32_bf16 v[12:15], v[138:141], v[188:191], v[12:15]
	v_mfma_f32_16x16x32_bf16 v[8:11], v[156:159], v[188:191], v[8:11]
	v_mfma_f32_16x16x32_bf16 v[60:63], v[152:155], v[168:171], v[60:63]
	v_mfma_f32_16x16x32_bf16 v[56:59], v[160:163], v[168:171], v[56:59]
	v_mfma_f32_16x16x32_bf16 v[44:47], v[152:155], v[176:179], v[44:47]
	v_mfma_f32_16x16x32_bf16 v[40:43], v[160:163], v[176:179], v[40:43]
	v_mfma_f32_16x16x32_bf16 v[28:31], v[152:155], v[184:187], v[28:31]
	v_mfma_f32_16x16x32_bf16 v[24:27], v[160:163], v[184:187], v[24:27]
	v_mfma_f32_16x16x32_bf16 v[12:15], v[152:155], v[202:205], v[12:15]
	v_mfma_f32_16x16x32_bf16 v[8:11], v[160:163], v[202:205], v[8:11]
	s_barrier
	s_add_u32 s20, s20, s2
	s_addc_u32 s21, s21, s3
	s_add_u32 s84, s20, 0x80
	s_mov_b32 m0, s87
	s_addc_u32 s85, s21, 0
	global_load_lds_dwordx4 v194, s[20:21]
	s_add_i32 m0, s87, 0x2000
	s_nop 0
	global_load_lds_dwordx4 v132, s[20:21]
	s_waitcnt vmcnt(6)
	s_barrier
; #define PG8_STAGE(bufoff, gbase, voff) do { _Pragma("unroll") for (int _i = 0; _i < 2; ++_i) \
;         __builtin_amdgcn_global_load_lds((const unsigned*)((const char*)(gbase) + (voff)[_i]), (LAS unsigned*)(lds + (bufoff) + ldsw + _i * 8192), 16, 0, 0); } while (0)
; #define PG8_LDA(dst, b, h) do { _Pragma("unroll") for (int m = 0; m < 4; ++m) _Pragma("unroll") for (int k = 0; k < 2; ++k) dst[m][k] = *(const LAS bf16x8*)(lds + PG8_SA(b, h) + aoff + m * 2048 + k * 1024); } while (0)
; #define PG8_LDB(dst, b, h) do { _Pragma("unroll") for (int n = 0; n < 2; ++n) _Pragma("unroll") for (int k = 0; k < 2; ++k) dst[n][k] = *(const LAS bf16x8*)(lds + PG8_SB(b, h) + boff + n * 2048 + k * 1024); } while (0)
; #define PG8_MMA(ai, bj, At, Bt) do { __builtin_amdgcn_s_setprio(1); _Pragma("unroll") for (int m = 0; m < 4; ++m) _Pragma("unroll") for (int n = 0; n < 2; ++n) _Pragma("unroll") for (int k = 0; k < 2; ++k) \
;         acc[ai][bj][m][n] = __builtin_amdgcn_mfma_f32_16x16x32_bf16(Bt[n][k], At[m][k], acc[ai][bj][m][n], 0, 0, 0); __builtin_amdgcn_s_setprio(0); } while (0)
; #define PG8_WAIT_V(n) asm volatile("s_waitcnt vmcnt(" #n ")" ::: "memory")
; #define PG8_WAIT_L(n) asm volatile("s_waitcnt lgkmcnt(" #n ")" ::: "memory")
; #define PG8_BAR __builtin_amdgcn_s_barrier()
; #define PG8_SCHED __builtin_amdgcn_sched_barrier(0)
; template <class Epi>
; __device__ __forceinline__ void gemm_phase(LAS unsigned char* lds, const Gemm g, const StaticOrder& S, const Epi& E) {
;     ...
;             PG8_WAIT_V(6); PG8_BAR; PG8_MMA(1, 1, At, B1); PG8_BAR;
;             PG8_LDB(B0, 1, 0); PG8_SCHED; PG8_LDA(At, 1, 0); PG8_STAGE(PG8_SA(0, 1), a2 + hstep, voffA);
;             PG8_WAIT_L(8); PG8_BAR; PG8_WAIT_L(0); PG8_MMA(0, 0, At, B0); PG8_BAR; PG8_SCHED;
;             PG8_LDB(B1, 1, 1); PG8_STAGE(PG8_SB(1, 0), b3, voffB);
	v_mfma_f32_16x16x32_bf16 v[52:55], v[206:209], v[164:167], v[52:55]
	v_mfma_f32_16x16x32_bf16 v[48:51], v[214:217], v[164:167], v[48:51]
	v_mfma_f32_16x16x32_bf16 v[36:39], v[206:209], v[172:175], v[36:39]
	v_mfma_f32_16x16x32_bf16 v[32:35], v[214:217], v[172:175], v[32:35]
	v_mfma_f32_16x16x32_bf16 v[20:23], v[206:209], v[180:183], v[20:23]
	v_mfma_f32_16x16x32_bf16 v[16:19], v[214:217], v[180:183], v[16:19]
	v_mfma_f32_16x16x32_bf16 v[4:7], v[206:209], v[188:191], v[4:7]
	v_mfma_f32_16x16x32_bf16 v[0:3], v[214:217], v[188:191], v[0:3]
	v_mfma_f32_16x16x32_bf16 v[52:55], v[210:213], v[168:171], v[52:55]
	v_mfma_f32_16x16x32_bf16 v[48:51], v[218:221], v[168:171], v[48:51]
	v_mfma_f32_16x16x32_bf16 v[36:39], v[210:213], v[176:179], v[36:39]
	v_mfma_f32_16x16x32_bf16 v[32:35], v[218:221], v[176:179], v[32:35]
	v_mfma_f32_16x16x32_bf16 v[20:23], v[210:213], v[184:187], v[20:23]
	v_mfma_f32_16x16x32_bf16 v[16:19], v[218:221], v[184:187], v[16:19]
	v_mfma_f32_16x16x32_bf16 v[4:7], v[210:213], v[202:205], v[4:7]
	v_mfma_f32_16x16x32_bf16 v[0:3], v[218:221], v[202:205], v[0:3]
	s_barrier
	ds_read_b128 v[138:141], v226
	ds_read_b128 v[152:155], v226 offset:1024
	ds_read_b128 v[156:159], v226 offset:2048
	ds_read_b128 v[160:163], v226 offset:3072
	s_add_u32 s18, s18, s2
	s_addc_u32 s19, s19, s3
	s_mov_b32 m0, s29
	ds_read_b128 v[164:167], v150 offset:32768
	ds_read_b128 v[168:171], v150 offset:33792
	ds_read_b128 v[172:175], v150 offset:34816
	ds_read_b128 v[176:179], v150 offset:35840
	ds_read_b128 v[180:183], v150 offset:36864
	ds_read_b128 v[184:187], v150 offset:37888
	ds_read_b128 v[188:191], v150 offset:38912
	global_load_lds_dwordx4 v128, s[18:19]
	s_mov_b32 m0, s30
	ds_read_b128 v[202:205], v150 offset:39936
	global_load_lds_dwordx4 v130, s[18:19]
	s_waitcnt lgkmcnt(8)
	s_barrier
	s_waitcnt lgkmcnt(0)
	v_mfma_f32_16x16x32_bf16 v[124:127], v[138:141], v[164:167], v[124:127]
	v_mfma_f32_16x16x32_bf16 v[120:123], v[156:159], v[164:167], v[120:123]
	v_mfma_f32_16x16x32_bf16 v[108:111], v[138:141], v[172:175], v[108:111]
	v_mfma_f32_16x16x32_bf16 v[104:107], v[156:159], v[172:175], v[104:107]
	v_mfma_f32_16x16x32_bf16 v[92:95], v[138:141], v[180:183], v[92:95]
	v_mfma_f32_16x16x32_bf16 v[88:91], v[156:159], v[180:183], v[88:91]
	v_mfma_f32_16x16x32_bf16 v[76:79], v[138:141], v[188:191], v[76:79]
	v_mfma_f32_16x16x32_bf16 v[72:75], v[156:159], v[188:191], v[72:75]
	v_mfma_f32_16x16x32_bf16 v[124:127], v[152:155], v[168:171], v[124:127]
	v_mfma_f32_16x16x32_bf16 v[120:123], v[160:163], v[168:171], v[120:123]
	v_mfma_f32_16x16x32_bf16 v[108:111], v[152:155], v[176:179], v[108:111]
	v_mfma_f32_16x16x32_bf16 v[104:107], v[160:163], v[176:179], v[104:107]
	v_mfma_f32_16x16x32_bf16 v[92:95], v[152:155], v[184:187], v[92:95]
	v_mfma_f32_16x16x32_bf16 v[88:91], v[160:163], v[184:187], v[88:91]
	v_mfma_f32_16x16x32_bf16 v[76:79], v[152:155], v[202:205], v[76:79]
	v_mfma_f32_16x16x32_bf16 v[72:75], v[160:163], v[202:205], v[72:75]
	s_barrier
	s_mov_b32 m0, s88
	ds_read_b128 v[206:209], v227
	ds_read_b128 v[210:213], v227 offset:1024
	ds_read_b128 v[214:217], v227 offset:2048
	global_load_lds_dwordx4 v194, s[80:81]
	s_add_i32 m0, s88, 0x2000
	ds_read_b128 v[218:221], v227 offset:3072
	global_load_lds_dwordx4 v132, s[80:81]
	s_barrier
; #define PG8_STAGE(bufoff, gbase, voff) do { _Pragma("unroll") for (int _i = 0; _i < 2; ++_i) \
;         __builtin_amdgcn_global_load_lds((const unsigned*)((const char*)(gbase) + (voff)[_i]), (LAS unsigned*)(lds + (bufoff) + ldsw + _i * 8192), 16, 0, 0); } while (0)
; #define PG8_LDA(dst, b, h) do { _Pragma("unroll") for (int m = 0; m < 4; ++m) _Pragma("unroll") for (int k = 0; k < 2; ++k) dst[m][k] = *(const LAS bf16x8*)(lds + PG8_SA(b, h) + aoff + m * 2048 + k * 1024); } while (0)
; #define PG8_MMA(ai, bj, At, Bt) do { __builtin_amdgcn_s_setprio(1); _Pragma("unroll") for (int m = 0; m < 4; ++m) _Pragma("unroll") for (int n = 0; n < 2; ++n) _Pragma("unroll") for (int k = 0; k < 2; ++k) \
;         acc[ai][bj][m][n] = __builtin_amdgcn_mfma_f32_16x16x32_bf16(Bt[n][k], At[m][k], acc[ai][bj][m][n], 0, 0, 0); __builtin_amdgcn_s_setprio(0); } while (0)
; #define PG8_WAIT_V(n) asm volatile("s_waitcnt vmcnt(" #n ")" ::: "memory")
; #define PG8_WAIT_L(n) asm volatile("s_waitcnt lgkmcnt(" #n ")" ::: "memory")
; #define PG8_BAR __builtin_amdgcn_s_barrier()
; #define PG8_SCHED __builtin_amdgcn_sched_barrier(0)
; template <class Epi>
; __device__ __forceinline__ void gemm_phase(LAS unsigned char* lds, const Gemm g, const StaticOrder& S, const Epi& E) {
;     ...
;             PG8_BAR; PG8_WAIT_L(0); PG8_MMA(0, 1, At, B1); PG8_BAR;
;             PG8_LDA(At, 1, 1); PG8_STAGE(PG8_SA(1, 0), a3, voffA);
;             PG8_BAR; PG8_WAIT_L(0); PG8_MMA(1, 0, At, B0); PG8_BAR; PG8_SCHED;
;             PG8_STAGE(PG8_SB(1, 1), b3 + hstep, voffB);
;             PG8_WAIT_V(6); PG8_BAR; PG8_MMA(1, 1, At, B1); PG8_BAR;
;         }
	s_waitcnt lgkmcnt(0)
	v_mfma_f32_16x16x32_bf16 v[116:119], v[206:209], v[164:167], v[116:119]
	v_mfma_f32_16x16x32_bf16 v[112:115], v[214:217], v[164:167], v[112:115]
	v_mfma_f32_16x16x32_bf16 v[100:103], v[206:209], v[172:175], v[100:103]
	v_mfma_f32_16x16x32_bf16 v[96:99], v[214:217], v[172:175], v[96:99]
	v_mfma_f32_16x16x32_bf16 v[84:87], v[206:209], v[180:183], v[84:87]
	v_mfma_f32_16x16x32_bf16 v[80:83], v[214:217], v[180:183], v[80:83]
	v_mfma_f32_16x16x32_bf16 v[68:71], v[206:209], v[188:191], v[68:71]
	v_mfma_f32_16x16x32_bf16 v[64:67], v[214:217], v[188:191], v[64:67]
	v_mfma_f32_16x16x32_bf16 v[116:119], v[210:213], v[168:171], v[116:119]
	v_mfma_f32_16x16x32_bf16 v[112:115], v[218:221], v[168:171], v[112:115]
	v_mfma_f32_16x16x32_bf16 v[100:103], v[210:213], v[176:179], v[100:103]
	v_mfma_f32_16x16x32_bf16 v[96:99], v[218:221], v[176:179], v[96:99]
	v_mfma_f32_16x16x32_bf16 v[84:87], v[210:213], v[184:187], v[84:87]
	v_mfma_f32_16x16x32_bf16 v[80:83], v[218:221], v[184:187], v[80:83]
	v_mfma_f32_16x16x32_bf16 v[68:71], v[210:213], v[202:205], v[68:71]
	v_mfma_f32_16x16x32_bf16 v[64:67], v[218:221], v[202:205], v[64:67]
	s_mov_b32 m0, s31
	s_barrier
	ds_read_b128 v[164:167], v150 offset:49152
	ds_read_b128 v[168:171], v150 offset:50176
	ds_read_b128 v[172:175], v150 offset:51200
	ds_read_b128 v[176:179], v150 offset:52224
	ds_read_b128 v[180:183], v150 offset:53248
	ds_read_b128 v[184:187], v150 offset:54272
	ds_read_b128 v[188:191], v150 offset:55296
	global_load_lds_dwordx4 v128, s[82:83]
	s_mov_b32 m0, s33
	ds_read_b128 v[202:205], v150 offset:56320
	global_load_lds_dwordx4 v130, s[82:83]
	s_barrier
	s_waitcnt lgkmcnt(0)
	v_mfma_f32_16x16x32_bf16 v[60:63], v[138:141], v[164:167], v[60:63]
	v_mfma_f32_16x16x32_bf16 v[56:59], v[156:159], v[164:167], v[56:59]
	v_mfma_f32_16x16x32_bf16 v[44:47], v[138:141], v[172:175], v[44:47]
	v_mfma_f32_16x16x32_bf16 v[40:43], v[156:159], v[172:175], v[40:43]
	v_mfma_f32_16x16x32_bf16 v[28:31], v[138:141], v[180:183], v[28:31]
	v_mfma_f32_16x16x32_bf16 v[24:27], v[156:159], v[180:183], v[24:27]
	v_mfma_f32_16x16x32_bf16 v[12:15], v[138:141], v[188:191], v[12:15]
	v_mfma_f32_16x16x32_bf16 v[8:11], v[156:159], v[188:191], v[8:11]
	v_mfma_f32_16x16x32_bf16 v[60:63], v[152:155], v[168:171], v[60:63]
	v_mfma_f32_16x16x32_bf16 v[56:59], v[160:163], v[168:171], v[56:59]
	v_mfma_f32_16x16x32_bf16 v[44:47], v[152:155], v[176:179], v[44:47]
	v_mfma_f32_16x16x32_bf16 v[40:43], v[160:163], v[176:179], v[40:43]
	v_mfma_f32_16x16x32_bf16 v[28:31], v[152:155], v[184:187], v[28:31]
	v_mfma_f32_16x16x32_bf16 v[24:27], v[160:163], v[184:187], v[24:27]
	v_mfma_f32_16x16x32_bf16 v[12:15], v[152:155], v[202:205], v[12:15]
	v_mfma_f32_16x16x32_bf16 v[8:11], v[160:163], v[202:205], v[8:11]
	s_barrier
	s_mov_b32 m0, s89
	s_nop 0
	global_load_lds_dwordx4 v194, s[84:85]
	s_add_i32 m0, s89, 0x2000
	s_nop 0
	global_load_lds_dwordx4 v132, s[84:85]
	s_waitcnt vmcnt(6)
	s_barrier
	v_mfma_f32_16x16x32_bf16 v[52:55], v[206:209], v[164:167], v[52:55]
	v_mfma_f32_16x16x32_bf16 v[48:51], v[214:217], v[164:167], v[48:51]
	v_mfma_f32_16x16x32_bf16 v[36:39], v[206:209], v[172:175], v[36:39]
	v_mfma_f32_16x16x32_bf16 v[32:35], v[214:217], v[172:175], v[32:35]
	v_mfma_f32_16x16x32_bf16 v[20:23], v[206:209], v[180:183], v[20:23]
	v_mfma_f32_16x16x32_bf16 v[16:19], v[214:217], v[180:183], v[16:19]
	v_mfma_f32_16x16x32_bf16 v[4:7], v[206:209], v[188:191], v[4:7]
	v_mfma_f32_16x16x32_bf16 v[0:3], v[214:217], v[188:191], v[0:3]
	v_mfma_f32_16x16x32_bf16 v[52:55], v[210:213], v[168:171], v[52:55]
	v_mfma_f32_16x16x32_bf16 v[48:51], v[218:221], v[168:171], v[48:51]
	v_mfma_f32_16x16x32_bf16 v[36:39], v[210:213], v[176:179], v[36:39]
	v_mfma_f32_16x16x32_bf16 v[32:35], v[218:221], v[176:179], v[32:35]
	v_mfma_f32_16x16x32_bf16 v[20:23], v[210:213], v[184:187], v[20:23]
	v_mfma_f32_16x16x32_bf16 v[16:19], v[218:221], v[184:187], v[16:19]
	v_mfma_f32_16x16x32_bf16 v[4:7], v[210:213], v[202:205], v[4:7]
	v_mfma_f32_16x16x32_bf16 v[0:3], v[218:221], v[202:205], v[0:3]
	s_add_u32 s42, s42, 0x100
	s_addc_u32 s43, s43, 0
	s_add_u32 s16, s16, 0x100
	s_addc_u32 s17, s17, 0
	s_cmp_ge_i32 s44, s34
	s_mov_b32 s18, s44
	s_barrier
	s_cbranch_scc0 .LBB0_165

; template <class Epi>
; __device__ __forceinline__ void gemm_phase(LAS unsigned char* lds, const Gemm g, const StaticOrder& S, const Epi& E) {
;     ...
;     f32x4 acc[2][2][4][2];
; #pragma unroll
;     for (int a = 0; a < 2; ++a)
; #pragma unroll
;         for (int b = 0; b < 2; ++b)
; #pragma unroll
;             for (int m = 0; m < 4; ++m)
; #pragma unroll
;                 for (int n = 0; n < 2; ++n) acc[a][b][m][n] = (f32x4){0.f, 0.f, 0.f, 0.f};
;     ...
; #pragma unroll
;         for (int a = 0; a < 2; ++a)
; #pragma unroll
;             for (int b = 0; b < 2; ++b)
; #pragma unroll
;                 for (int m = 0; m < 4; ++m)
; #pragma unroll
;                     for (int n = 0; n < 2; ++n) acc[a][b][m][n] = (f32x4){0.f, 0.f, 0.f, 0.f};
;         cur = nxt; cA = nA; cB = nB; ++ui;
.LBB0_526:
	v_mov_b32_e32 v127, 0
	s_andn2_b64 vcc, exec, s[6:7]
	v_mov_b32_e32 v126, v127
	v_mov_b32_e32 v125, v127
	v_mov_b32_e32 v124, v127
	v_mov_b32_e32 v123, v127
	v_mov_b32_e32 v122, v127
	v_mov_b32_e32 v121, v127
	v_mov_b32_e32 v120, v127
	v_mov_b32_e32 v111, v127
	v_mov_b32_e32 v110, v127
	v_mov_b32_e32 v109, v127
	v_mov_b32_e32 v108, v127
	v_mov_b32_e32 v107, v127
	v_mov_b32_e32 v106, v127
	v_mov_b32_e32 v105, v127
	v_mov_b32_e32 v104, v127
	v_mov_b32_e32 v95, v127
	v_mov_b32_e32 v94, v127
	v_mov_b32_e32 v93, v127
	v_mov_b32_e32 v92, v127
	v_mov_b32_e32 v91, v127
	v_mov_b32_e32 v90, v127
	v_mov_b32_e32 v89, v127
	v_mov_b32_e32 v88, v127
	v_mov_b32_e32 v79, v127
	v_mov_b32_e32 v78, v127
	v_mov_b32_e32 v77, v127
	v_mov_b32_e32 v76, v127
	v_mov_b32_e32 v75, v127
	v_mov_b32_e32 v74, v127
	v_mov_b32_e32 v73, v127
	v_mov_b32_e32 v72, v127
	v_mov_b32_e32 v119, v127
	v_mov_b32_e32 v118, v127
	v_mov_b32_e32 v117, v127
	v_mov_b32_e32 v116, v127
	v_mov_b32_e32 v115, v127
	v_mov_b32_e32 v114, v127
	v_mov_b32_e32 v113, v127
	v_mov_b32_e32 v112, v127
	v_mov_b32_e32 v103, v127
	v_mov_b32_e32 v102, v127
	v_mov_b32_e32 v101, v127
	v_mov_b32_e32 v100, v127
	v_mov_b32_e32 v99, v127
	v_mov_b32_e32 v98, v127
	v_mov_b32_e32 v97, v127
	v_mov_b32_e32 v96, v127
	v_mov_b32_e32 v87, v127
	v_mov_b32_e32 v86, v127
	v_mov_b32_e32 v85, v127
	v_mov_b32_e32 v84, v127
	v_mov_b32_e32 v83, v127
	v_mov_b32_e32 v82, v127
	v_mov_b32_e32 v81, v127
	v_mov_b32_e32 v80, v127
	v_mov_b32_e32 v71, v127
	v_mov_b32_e32 v70, v127
	v_mov_b32_e32 v69, v127
	v_mov_b32_e32 v68, v127
	v_mov_b32_e32 v67, v127
	v_mov_b32_e32 v66, v127
	v_mov_b32_e32 v65, v127
	v_mov_b32_e32 v64, v127
	v_mov_b32_e32 v63, v127
	v_mov_b32_e32 v62, v127
	v_mov_b32_e32 v61, v127
	v_mov_b32_e32 v60, v127
	v_mov_b32_e32 v59, v127
	v_mov_b32_e32 v58, v127
	v_mov_b32_e32 v57, v127
	v_mov_b32_e32 v56, v127
	v_mov_b32_e32 v47, v127
	v_mov_b32_e32 v46, v127
	v_mov_b32_e32 v45, v127
	v_mov_b32_e32 v44, v127
	v_mov_b32_e32 v43, v127
	v_mov_b32_e32 v42, v127
	v_mov_b32_e32 v41, v127
	v_mov_b32_e32 v40, v127
	v_mov_b32_e32 v31, v127
	v_mov_b32_e32 v30, v127
	v_mov_b32_e32 v29, v127
	v_mov_b32_e32 v28, v127
	v_mov_b32_e32 v27, v127
	v_mov_b32_e32 v26, v127
	v_mov_b32_e32 v25, v127
	v_mov_b32_e32 v24, v127
	v_mov_b32_e32 v15, v127
	v_mov_b32_e32 v14, v127
	v_mov_b32_e32 v13, v127
	v_mov_b32_e32 v12, v127
	v_mov_b32_e32 v11, v127
	v_mov_b32_e32 v10, v127
	v_mov_b32_e32 v9, v127
	v_mov_b32_e32 v8, v127
	v_mov_b32_e32 v55, v127
	v_mov_b32_e32 v54, v127
	v_mov_b32_e32 v53, v127
	v_mov_b32_e32 v52, v127
	v_mov_b32_e32 v51, v127
	v_mov_b32_e32 v50, v127
	v_mov_b32_e32 v49, v127
	v_mov_b32_e32 v48, v127
	v_mov_b32_e32 v39, v127
	v_mov_b32_e32 v38, v127
	v_mov_b32_e32 v37, v127
	v_mov_b32_e32 v36, v127
	v_mov_b32_e32 v35, v127
	v_mov_b32_e32 v34, v127
	v_mov_b32_e32 v33, v127
	v_mov_b32_e32 v32, v127
	v_mov_b32_e32 v23, v127
	v_mov_b32_e32 v22, v127
	v_mov_b32_e32 v21, v127
	v_mov_b32_e32 v20, v127
	v_mov_b32_e32 v19, v127
	v_mov_b32_e32 v18, v127
	v_mov_b32_e32 v17, v127
	v_mov_b32_e32 v16, v127
	v_mov_b32_e32 v7, v127
	v_mov_b32_e32 v6, v127
	v_mov_b32_e32 v5, v127
	v_mov_b32_e32 v4, v127
	v_mov_b32_e32 v3, v127
	v_mov_b32_e32 v2, v127
	v_mov_b32_e32 v1, v127
	v_mov_b32_e32 v0, v127
	s_cbranch_vccnz .LBB0_529
	s_add_u32 s40, s18, 0x100
	s_addc_u32 s41, s19, 0
	s_add_u32 s16, s16, 0x80
	v_mov_b32_e32 v0, 0
	s_addc_u32 s17, s17, 0
	s_mov_b32 s18, 0
	v_mov_b32_e32 v1, v0
	v_mov_b32_e32 v2, v0
	v_mov_b32_e32 v3, v0
	v_mov_b32_e32 v4, v0
	v_mov_b32_e32 v5, v0
	v_mov_b32_e32 v6, v0
	v_mov_b32_e32 v7, v0
	v_mov_b32_e32 v16, v0
	v_mov_b32_e32 v17, v0
	v_mov_b32_e32 v18, v0
	v_mov_b32_e32 v19, v0
	v_mov_b32_e32 v20, v0
	v_mov_b32_e32 v21, v0
	v_mov_b32_e32 v22, v0
	v_mov_b32_e32 v23, v0
	v_mov_b32_e32 v32, v0
	v_mov_b32_e32 v33, v0
	v_mov_b32_e32 v34, v0
	v_mov_b32_e32 v35, v0
	v_mov_b32_e32 v36, v0
	v_mov_b32_e32 v37, v0
	v_mov_b32_e32 v38, v0
	v_mov_b32_e32 v39, v0
	v_mov_b32_e32 v48, v0
	v_mov_b32_e32 v49, v0
	v_mov_b32_e32 v50, v0
	v_mov_b32_e32 v51, v0
	v_mov_b32_e32 v52, v0
	v_mov_b32_e32 v53, v0
	v_mov_b32_e32 v54, v0
	v_mov_b32_e32 v55, v0
	v_mov_b32_e32 v8, v0
	v_mov_b32_e32 v9, v0
	v_mov_b32_e32 v10, v0
	v_mov_b32_e32 v11, v0
	v_mov_b32_e32 v12, v0
	v_mov_b32_e32 v13, v0
	v_mov_b32_e32 v14, v0
	v_mov_b32_e32 v15, v0
	v_mov_b32_e32 v24, v0
	v_mov_b32_e32 v25, v0
	v_mov_b32_e32 v26, v0
	v_mov_b32_e32 v27, v0
	v_mov_b32_e32 v28, v0
	v_mov_b32_e32 v29, v0
	v_mov_b32_e32 v30, v0
	v_mov_b32_e32 v31, v0
	v_mov_b32_e32 v40, v0
	v_mov_b32_e32 v41, v0
	v_mov_b32_e32 v42, v0
	v_mov_b32_e32 v43, v0
	v_mov_b32_e32 v44, v0
	v_mov_b32_e32 v45, v0
	v_mov_b32_e32 v46, v0
	v_mov_b32_e32 v47, v0
	v_mov_b32_e32 v56, v0
	v_mov_b32_e32 v57, v0
	v_mov_b32_e32 v58, v0
	v_mov_b32_e32 v59, v0
	v_mov_b32_e32 v60, v0
	v_mov_b32_e32 v61, v0
	v_mov_b32_e32 v62, v0
	v_mov_b32_e32 v63, v0
	v_mov_b32_e32 v64, v0
	v_mov_b32_e32 v65, v0
	v_mov_b32_e32 v66, v0
	v_mov_b32_e32 v67, v0
	v_mov_b32_e32 v68, v0
	v_mov_b32_e32 v69, v0
	v_mov_b32_e32 v70, v0
	v_mov_b32_e32 v71, v0
	v_mov_b32_e32 v80, v0
	v_mov_b32_e32 v81, v0
	v_mov_b32_e32 v82, v0
	v_mov_b32_e32 v83, v0
	v_mov_b32_e32 v84, v0
	v_mov_b32_e32 v85, v0
	v_mov_b32_e32 v86, v0
	v_mov_b32_e32 v87, v0
	v_mov_b32_e32 v96, v0
	v_mov_b32_e32 v97, v0
	v_mov_b32_e32 v98, v0
	v_mov_b32_e32 v99, v0
	v_mov_b32_e32 v100, v0
	v_mov_b32_e32 v101, v0
	v_mov_b32_e32 v102, v0
	v_mov_b32_e32 v103, v0
	v_mov_b32_e32 v112, v0
	v_mov_b32_e32 v113, v0
	v_mov_b32_e32 v114, v0
	v_mov_b32_e32 v115, v0
	v_mov_b32_e32 v116, v0
	v_mov_b32_e32 v117, v0
	v_mov_b32_e32 v118, v0
	v_mov_b32_e32 v119, v0
	v_mov_b32_e32 v72, v0
	v_mov_b32_e32 v73, v0
	v_mov_b32_e32 v74, v0
	v_mov_b32_e32 v75, v0
	v_mov_b32_e32 v76, v0
	v_mov_b32_e32 v77, v0
	v_mov_b32_e32 v78, v0
	v_mov_b32_e32 v79, v0
	v_mov_b32_e32 v88, v0
	v_mov_b32_e32 v89, v0
	v_mov_b32_e32 v90, v0
	v_mov_b32_e32 v91, v0
	v_mov_b32_e32 v92, v0
	v_mov_b32_e32 v93, v0
	v_mov_b32_e32 v94, v0
	v_mov_b32_e32 v95, v0
	v_mov_b32_e32 v104, v0
	v_mov_b32_e32 v105, v0
	v_mov_b32_e32 v106, v0
	v_mov_b32_e32 v107, v0
	v_mov_b32_e32 v108, v0
	v_mov_b32_e32 v109, v0
	v_mov_b32_e32 v110, v0
	v_mov_b32_e32 v111, v0
	v_mov_b32_e32 v120, v0
	v_mov_b32_e32 v121, v0
	v_mov_b32_e32 v122, v0
	v_mov_b32_e32 v123, v0
	v_mov_b32_e32 v124, v0
	v_mov_b32_e32 v125, v0
	v_mov_b32_e32 v126, v0
	v_mov_b32_e32 v127, v0
	s_mov_b64 s[46:47], 0x80
	v_add_u32_e32 v224, 0x10000, v144
	v_add_u32_e32 v225, 0x14000, v144
	v_add_u32_e32 v226, 0x18000, v144
	v_add_u32_e32 v227, 0x1c000, v144
	s_add_i32 s86, s24, 0x10000
	s_add_i32 s87, s24, 0x14000
	s_add_i32 s88, s24, 0x18000
	s_add_i32 s89, s24, 0x1c000
; #define PG8_STAGE(bufoff, gbase, voff) do { _Pragma("unroll") for (int _i = 0; _i < 2; ++_i) \
;         __builtin_amdgcn_global_load_lds((const unsigned*)((const char*)(gbase) + (voff)[_i]), (LAS unsigned*)(lds + (bufoff) + ldsw + _i * 8192), 16, 0, 0); } while (0)
; #define PG8_LDA(dst, b, h) do { _Pragma("unroll") for (int m = 0; m < 4; ++m) _Pragma("unroll") for (int k = 0; k < 2; ++k) dst[m][k] = *(const LAS bf16x8*)(lds + PG8_SA(b, h) + aoff + m * 2048 + k * 1024); } while (0)
; #define PG8_LDB(dst, b, h) do { _Pragma("unroll") for (int n = 0; n < 2; ++n) _Pragma("unroll") for (int k = 0; k < 2; ++k) dst[n][k] = *(const LAS bf16x8*)(lds + PG8_SB(b, h) + boff + n * 2048 + k * 1024); } while (0)
; #define PG8_WAIT_V(n) asm volatile("s_waitcnt vmcnt(" #n ")" ::: "memory")
; #define PG8_WAIT_L(n) asm volatile("s_waitcnt lgkmcnt(" #n ")" ::: "memory")
; #define PG8_BAR __builtin_amdgcn_s_barrier()
; #define PG8_SCHED __builtin_amdgcn_sched_barrier(0)
; template <class Epi>
; __device__ __forceinline__ void gemm_phase(LAS unsigned char* lds, const Gemm g, const StaticOrder& S, const Epi& E) {
;     ...
;         const bool has_next = S.next(ui + 1, nxt);
;         const char* nA = has_next ? (const char*)g.A + (size_t)nxt.pm * tstep : cA; const char* nB = has_next ? (const char*)g.Bt + (size_t)nxt.pn * tstep : cB;
;         for (int t = 0; t < nt; t += 2) {
;             const bool last = (t == nt - 2);
;             const char* a1 = cA + (size_t)(t + 1) * kstep;
;             const char* a2 = last ? nA : cA + (size_t)(t + 2) * kstep; const char* b2 = last ? nB : cB + (size_t)(t + 2) * kstep;
;             const char* a3 = a2 + kstep; const char* b3 = b2 + kstep;
;             PG8_LDB(B0, 0, 0); PG8_SCHED; PG8_LDA(At, 0, 0); PG8_STAGE(PG8_SA(1, 1), a1 + hstep, voffA);
;             PG8_WAIT_L(8); PG8_BAR; PG8_WAIT_L(0); PG8_MMA(0, 0, At, B0); PG8_BAR; PG8_SCHED;
;             PG8_LDB(B1, 0, 1); PG8_STAGE(PG8_SB(0, 0), b2, voffB);
;             PG8_BAR; PG8_WAIT_L(0); PG8_MMA(0, 1, At, B1); PG8_BAR;
;             PG8_LDA(At, 0, 1); PG8_STAGE(PG8_SA(0, 0), a2, voffA);
;             PG8_BAR; PG8_WAIT_L(0); PG8_MMA(1, 0, At, B0); PG8_BAR; PG8_SCHED;
;             PG8_STAGE(PG8_SB(0, 1), b2 + hstep, voffB);
;             PG8_WAIT_V(6); PG8_BAR; PG8_MMA(1, 1, At, B1); PG8_BAR;
.LBB0_528:
	s_add_i32 s42, s18, 2
	s_add_u32 s20, s16, 0x80
	s_addc_u32 s19, s17, 0
	ds_read_b128 v[138:141], v224
	ds_read_b128 v[150:153], v224 offset:1024
	ds_read_b128 v[154:157], v224 offset:2048
	ds_read_b128 v[158:161], v224 offset:3072
	s_cmp_eq_u32 s33, s18
	s_cselect_b32 s18, s10, s20
	s_cselect_b32 s19, s11, s19
	s_cselect_b32 s21, s13, s41
	s_cselect_b32 s20, s12, s40
	s_add_i32 m0, s25, 0xc000
	ds_read_b128 v[162:165], v148
	ds_read_b128 v[166:169], v148 offset:1024
	ds_read_b128 v[170:173], v148 offset:2048
	ds_read_b128 v[174:177], v148 offset:3072
	ds_read_b128 v[178:181], v148 offset:4096
	ds_read_b128 v[182:185], v148 offset:5120
	ds_read_b128 v[186:189], v148 offset:6144
	global_load_lds_dwordx4 v136, s[16:17]
	s_add_i32 m0, s25, 0xe000
	ds_read_b128 v[202:205], v148 offset:7168
	global_load_lds_dwordx4 v134, s[16:17]
	s_waitcnt lgkmcnt(8)
	s_barrier
	s_waitcnt lgkmcnt(0)
	v_mfma_f32_16x16x32_bf16 v[124:127], v[138:141], v[162:165], v[124:127]
	v_mfma_f32_16x16x32_bf16 v[120:123], v[154:157], v[162:165], v[120:123]
	v_mfma_f32_16x16x32_bf16 v[108:111], v[138:141], v[170:173], v[108:111]
	v_mfma_f32_16x16x32_bf16 v[104:107], v[154:157], v[170:173], v[104:107]
	v_mfma_f32_16x16x32_bf16 v[92:95], v[138:141], v[178:181], v[92:95]
	v_mfma_f32_16x16x32_bf16 v[88:91], v[154:157], v[178:181], v[88:91]
	v_mfma_f32_16x16x32_bf16 v[76:79], v[138:141], v[186:189], v[76:79]
	v_mfma_f32_16x16x32_bf16 v[72:75], v[154:157], v[186:189], v[72:75]
	v_mfma_f32_16x16x32_bf16 v[124:127], v[150:153], v[166:169], v[124:127]
	v_mfma_f32_16x16x32_bf16 v[120:123], v[158:161], v[166:169], v[120:123]
	v_mfma_f32_16x16x32_bf16 v[108:111], v[150:153], v[174:177], v[108:111]
	v_mfma_f32_16x16x32_bf16 v[104:107], v[158:161], v[174:177], v[104:107]
	v_mfma_f32_16x16x32_bf16 v[92:95], v[150:153], v[182:185], v[92:95]
	v_mfma_f32_16x16x32_bf16 v[88:91], v[158:161], v[182:185], v[88:91]
	v_mfma_f32_16x16x32_bf16 v[76:79], v[150:153], v[202:205], v[76:79]
	v_mfma_f32_16x16x32_bf16 v[72:75], v[158:161], v[202:205], v[72:75]
	s_barrier
	s_add_u32 s80, s20, 0x80
	s_addc_u32 s81, s21, 0
	s_mov_b32 m0, s86
	ds_read_b128 v[206:209], v225
	ds_read_b128 v[210:213], v225 offset:1024
	ds_read_b128 v[214:217], v225 offset:2048
	global_load_lds_dwordx4 v194, s[20:21]
	s_add_i32 m0, s86, 0x2000
	ds_read_b128 v[218:221], v225 offset:3072
	global_load_lds_dwordx4 v132, s[20:21]
	s_barrier
	s_waitcnt lgkmcnt(0)
	v_mfma_f32_16x16x32_bf16 v[116:119], v[206:209], v[162:165], v[116:119]
	v_mfma_f32_16x16x32_bf16 v[112:115], v[214:217], v[162:165], v[112:115]
	v_mfma_f32_16x16x32_bf16 v[100:103], v[206:209], v[170:173], v[100:103]
	v_mfma_f32_16x16x32_bf16 v[96:99], v[214:217], v[170:173], v[96:99]
	v_mfma_f32_16x16x32_bf16 v[84:87], v[206:209], v[178:181], v[84:87]
	v_mfma_f32_16x16x32_bf16 v[80:83], v[214:217], v[178:181], v[80:83]
	v_mfma_f32_16x16x32_bf16 v[68:71], v[206:209], v[186:189], v[68:71]
	v_mfma_f32_16x16x32_bf16 v[64:67], v[214:217], v[186:189], v[64:67]
	v_mfma_f32_16x16x32_bf16 v[116:119], v[210:213], v[166:169], v[116:119]
	v_mfma_f32_16x16x32_bf16 v[112:115], v[218:221], v[166:169], v[112:115]
	v_mfma_f32_16x16x32_bf16 v[100:103], v[210:213], v[174:177], v[100:103]
	v_mfma_f32_16x16x32_bf16 v[96:99], v[218:221], v[174:177], v[96:99]
	v_mfma_f32_16x16x32_bf16 v[84:87], v[210:213], v[182:185], v[84:87]
	v_mfma_f32_16x16x32_bf16 v[80:83], v[218:221], v[182:185], v[80:83]
	v_mfma_f32_16x16x32_bf16 v[68:71], v[210:213], v[202:205], v[68:71]
	v_mfma_f32_16x16x32_bf16 v[64:67], v[218:221], v[202:205], v[64:67]
	s_mov_b32 m0, s25
	s_add_u32 s82, s18, 0x80
	s_addc_u32 s83, s19, 0
	s_barrier
	ds_read_b128 v[162:165], v148 offset:16384
	ds_read_b128 v[166:169], v148 offset:17408
	ds_read_b128 v[170:173], v148 offset:18432
	ds_read_b128 v[174:177], v148 offset:19456
	ds_read_b128 v[178:181], v148 offset:20480
	ds_read_b128 v[182:185], v148 offset:21504
	ds_read_b128 v[186:189], v148 offset:22528
	global_load_lds_dwordx4 v128, s[18:19]
	s_mov_b32 m0, s26
	ds_read_b128 v[202:205], v148 offset:23552
	global_load_lds_dwordx4 v130, s[18:19]
	s_barrier
	s_waitcnt lgkmcnt(0)
	v_mfma_f32_16x16x32_bf16 v[60:63], v[138:141], v[162:165], v[60:63]
	v_mfma_f32_16x16x32_bf16 v[56:59], v[154:157], v[162:165], v[56:59]
	v_mfma_f32_16x16x32_bf16 v[44:47], v[138:141], v[170:173], v[44:47]
	v_mfma_f32_16x16x32_bf16 v[40:43], v[154:157], v[170:173], v[40:43]
	v_mfma_f32_16x16x32_bf16 v[28:31], v[138:141], v[178:181], v[28:31]
	v_mfma_f32_16x16x32_bf16 v[24:27], v[154:157], v[178:181], v[24:27]
	v_mfma_f32_16x16x32_bf16 v[12:15], v[138:141], v[186:189], v[12:15]
	v_mfma_f32_16x16x32_bf16 v[8:11], v[154:157], v[186:189], v[8:11]
	v_mfma_f32_16x16x32_bf16 v[60:63], v[150:153], v[166:169], v[60:63]
	v_mfma_f32_16x16x32_bf16 v[56:59], v[158:161], v[166:169], v[56:59]
	v_mfma_f32_16x16x32_bf16 v[44:47], v[150:153], v[174:177], v[44:47]
	v_mfma_f32_16x16x32_bf16 v[40:43], v[158:161], v[174:177], v[40:43]
	v_mfma_f32_16x16x32_bf16 v[28:31], v[150:153], v[182:185], v[28:31]
	v_mfma_f32_16x16x32_bf16 v[24:27], v[158:161], v[182:185], v[24:27]
	v_mfma_f32_16x16x32_bf16 v[12:15], v[150:153], v[202:205], v[12:15]
	v_mfma_f32_16x16x32_bf16 v[8:11], v[158:161], v[202:205], v[8:11]
	s_barrier
	s_add_u32 s20, s20, s2
	s_addc_u32 s21, s21, s3
	s_add_u32 s84, s20, 0x80
	s_mov_b32 m0, s87
	s_addc_u32 s85, s21, 0
	global_load_lds_dwordx4 v194, s[20:21]
	s_add_i32 m0, s87, 0x2000
	s_nop 0
	global_load_lds_dwordx4 v132, s[20:21]
	s_waitcnt vmcnt(6)
	s_barrier
; #define PG8_STAGE(bufoff, gbase, voff) do { _Pragma("unroll") for (int _i = 0; _i < 2; ++_i) \
;         __builtin_amdgcn_global_load_lds((const unsigned*)((const char*)(gbase) + (voff)[_i]), (LAS unsigned*)(lds + (bufoff) + ldsw + _i * 8192), 16, 0, 0); } while (0)
; #define PG8_LDA(dst, b, h) do { _Pragma("unroll") for (int m = 0; m < 4; ++m) _Pragma("unroll") for (int k = 0; k < 2; ++k) dst[m][k] = *(const LAS bf16x8*)(lds + PG8_SA(b, h) + aoff + m * 2048 + k * 1024); } while (0)
; #define PG8_LDB(dst, b, h) do { _Pragma("unroll") for (int n = 0; n < 2; ++n) _Pragma("unroll") for (int k = 0; k < 2; ++k) dst[n][k] = *(const LAS bf16x8*)(lds + PG8_SB(b, h) + boff + n * 2048 + k * 1024); } while (0)
; #define PG8_MMA(ai, bj, At, Bt) do { __builtin_amdgcn_s_setprio(1); _Pragma("unroll") for (int m = 0; m < 4; ++m) _Pragma("unroll") for (int n = 0; n < 2; ++n) _Pragma("unroll") for (int k = 0; k < 2; ++k) \
;         acc[ai][bj][m][n] = __builtin_amdgcn_mfma_f32_16x16x32_bf16(Bt[n][k], At[m][k], acc[ai][bj][m][n], 0, 0, 0); __builtin_amdgcn_s_setprio(0); } while (0)
; #define PG8_WAIT_V(n) asm volatile("s_waitcnt vmcnt(" #n ")" ::: "memory")
; #define PG8_WAIT_L(n) asm volatile("s_waitcnt lgkmcnt(" #n ")" ::: "memory")
; #define PG8_BAR __builtin_amdgcn_s_barrier()
; #define PG8_SCHED __builtin_amdgcn_sched_barrier(0)
; template <class Epi>
; __device__ __forceinline__ void gemm_phase(LAS unsigned char* lds, const Gemm g, const StaticOrder& S, const Epi& E) {
;     ...
;             PG8_WAIT_V(6); PG8_BAR; PG8_MMA(1, 1, At, B1); PG8_BAR;
;             PG8_LDB(B0, 1, 0); PG8_SCHED; PG8_LDA(At, 1, 0); PG8_STAGE(PG8_SA(0, 1), a2 + hstep, voffA);
;             PG8_WAIT_L(8); PG8_BAR; PG8_WAIT_L(0); PG8_MMA(0, 0, At, B0); PG8_BAR; PG8_SCHED;
;             PG8_LDB(B1, 1, 1); PG8_STAGE(PG8_SB(1, 0), b3, voffB);
	v_mfma_f32_16x16x32_bf16 v[52:55], v[206:209], v[162:165], v[52:55]
	v_mfma_f32_16x16x32_bf16 v[48:51], v[214:217], v[162:165], v[48:51]
	v_mfma_f32_16x16x32_bf16 v[36:39], v[206:209], v[170:173], v[36:39]
	v_mfma_f32_16x16x32_bf16 v[32:35], v[214:217], v[170:173], v[32:35]
	v_mfma_f32_16x16x32_bf16 v[20:23], v[206:209], v[178:181], v[20:23]
	v_mfma_f32_16x16x32_bf16 v[16:19], v[214:217], v[178:181], v[16:19]
	v_mfma_f32_16x16x32_bf16 v[4:7], v[206:209], v[186:189], v[4:7]
	v_mfma_f32_16x16x32_bf16 v[0:3], v[214:217], v[186:189], v[0:3]
	v_mfma_f32_16x16x32_bf16 v[52:55], v[210:213], v[166:169], v[52:55]
	v_mfma_f32_16x16x32_bf16 v[48:51], v[218:221], v[166:169], v[48:51]
	v_mfma_f32_16x16x32_bf16 v[36:39], v[210:213], v[174:177], v[36:39]
	v_mfma_f32_16x16x32_bf16 v[32:35], v[218:221], v[174:177], v[32:35]
	v_mfma_f32_16x16x32_bf16 v[20:23], v[210:213], v[182:185], v[20:23]
	v_mfma_f32_16x16x32_bf16 v[16:19], v[218:221], v[182:185], v[16:19]
	v_mfma_f32_16x16x32_bf16 v[4:7], v[210:213], v[202:205], v[4:7]
	v_mfma_f32_16x16x32_bf16 v[0:3], v[218:221], v[202:205], v[0:3]
	s_barrier
	ds_read_b128 v[138:141], v226
	ds_read_b128 v[150:153], v226 offset:1024
	ds_read_b128 v[154:157], v226 offset:2048
	ds_read_b128 v[158:161], v226 offset:3072
	s_add_u32 s18, s18, s2
	s_addc_u32 s19, s19, s3
	s_mov_b32 m0, s27
	ds_read_b128 v[162:165], v148 offset:32768
	ds_read_b128 v[166:169], v148 offset:33792
	ds_read_b128 v[170:173], v148 offset:34816
	ds_read_b128 v[174:177], v148 offset:35840
	ds_read_b128 v[178:181], v148 offset:36864
	ds_read_b128 v[182:185], v148 offset:37888
	ds_read_b128 v[186:189], v148 offset:38912
	global_load_lds_dwordx4 v128, s[18:19]
	s_mov_b32 m0, s28
	ds_read_b128 v[202:205], v148 offset:39936
	global_load_lds_dwordx4 v130, s[18:19]
	s_waitcnt lgkmcnt(8)
	s_barrier
	s_waitcnt lgkmcnt(0)
	v_mfma_f32_16x16x32_bf16 v[124:127], v[138:141], v[162:165], v[124:127]
	v_mfma_f32_16x16x32_bf16 v[120:123], v[154:157], v[162:165], v[120:123]
	v_mfma_f32_16x16x32_bf16 v[108:111], v[138:141], v[170:173], v[108:111]
	v_mfma_f32_16x16x32_bf16 v[104:107], v[154:157], v[170:173], v[104:107]
	v_mfma_f32_16x16x32_bf16 v[92:95], v[138:141], v[178:181], v[92:95]
	v_mfma_f32_16x16x32_bf16 v[88:91], v[154:157], v[178:181], v[88:91]
	v_mfma_f32_16x16x32_bf16 v[76:79], v[138:141], v[186:189], v[76:79]
	v_mfma_f32_16x16x32_bf16 v[72:75], v[154:157], v[186:189], v[72:75]
	v_mfma_f32_16x16x32_bf16 v[124:127], v[150:153], v[166:169], v[124:127]
	v_mfma_f32_16x16x32_bf16 v[120:123], v[158:161], v[166:169], v[120:123]
	v_mfma_f32_16x16x32_bf16 v[108:111], v[150:153], v[174:177], v[108:111]
	v_mfma_f32_16x16x32_bf16 v[104:107], v[158:161], v[174:177], v[104:107]
	v_mfma_f32_16x16x32_bf16 v[92:95], v[150:153], v[182:185], v[92:95]
	v_mfma_f32_16x16x32_bf16 v[88:91], v[158:161], v[182:185], v[88:91]
	v_mfma_f32_16x16x32_bf16 v[76:79], v[150:153], v[202:205], v[76:79]
	v_mfma_f32_16x16x32_bf16 v[72:75], v[158:161], v[202:205], v[72:75]
	s_barrier
	s_mov_b32 m0, s88
	ds_read_b128 v[206:209], v227
	ds_read_b128 v[210:213], v227 offset:1024
	ds_read_b128 v[214:217], v227 offset:2048
	global_load_lds_dwordx4 v194, s[80:81]
	s_add_i32 m0, s88, 0x2000
	ds_read_b128 v[218:221], v227 offset:3072
	global_load_lds_dwordx4 v132, s[80:81]
	s_barrier
; #define PG8_STAGE(bufoff, gbase, voff) do { _Pragma("unroll") for (int _i = 0; _i < 2; ++_i) \
;         __builtin_amdgcn_global_load_lds((const unsigned*)((const char*)(gbase) + (voff)[_i]), (LAS unsigned*)(lds + (bufoff) + ldsw + _i * 8192), 16, 0, 0); } while (0)
; #define PG8_LDA(dst, b, h) do { _Pragma("unroll") for (int m = 0; m < 4; ++m) _Pragma("unroll") for (int k = 0; k < 2; ++k) dst[m][k] = *(const LAS bf16x8*)(lds + PG8_SA(b, h) + aoff + m * 2048 + k * 1024); } while (0)
; #define PG8_MMA(ai, bj, At, Bt) do { __builtin_amdgcn_s_setprio(1); _Pragma("unroll") for (int m = 0; m < 4; ++m) _Pragma("unroll") for (int n = 0; n < 2; ++n) _Pragma("unroll") for (int k = 0; k < 2; ++k) \
;         acc[ai][bj][m][n] = __builtin_amdgcn_mfma_f32_16x16x32_bf16(Bt[n][k], At[m][k], acc[ai][bj][m][n], 0, 0, 0); __builtin_amdgcn_s_setprio(0); } while (0)
; #define PG8_WAIT_V(n) asm volatile("s_waitcnt vmcnt(" #n ")" ::: "memory")
; #define PG8_WAIT_L(n) asm volatile("s_waitcnt lgkmcnt(" #n ")" ::: "memory")
; #define PG8_BAR __builtin_amdgcn_s_barrier()
; #define PG8_SCHED __builtin_amdgcn_sched_barrier(0)
; template <class Epi>
; __device__ __forceinline__ void gemm_phase(LAS unsigned char* lds, const Gemm g, const StaticOrder& S, const Epi& E) {
;     ...
;             PG8_BAR; PG8_WAIT_L(0); PG8_MMA(0, 1, At, B1); PG8_BAR;
;             PG8_LDA(At, 1, 1); PG8_STAGE(PG8_SA(1, 0), a3, voffA);
;             PG8_BAR; PG8_WAIT_L(0); PG8_MMA(1, 0, At, B0); PG8_BAR; PG8_SCHED;
;             PG8_STAGE(PG8_SB(1, 1), b3 + hstep, voffB);
;             PG8_WAIT_V(6); PG8_BAR; PG8_MMA(1, 1, At, B1); PG8_BAR;
;         }
	s_waitcnt lgkmcnt(0)
	v_mfma_f32_16x16x32_bf16 v[116:119], v[206:209], v[162:165], v[116:119]
	v_mfma_f32_16x16x32_bf16 v[112:115], v[214:217], v[162:165], v[112:115]
	v_mfma_f32_16x16x32_bf16 v[100:103], v[206:209], v[170:173], v[100:103]
	v_mfma_f32_16x16x32_bf16 v[96:99], v[214:217], v[170:173], v[96:99]
	v_mfma_f32_16x16x32_bf16 v[84:87], v[206:209], v[178:181], v[84:87]
	v_mfma_f32_16x16x32_bf16 v[80:83], v[214:217], v[178:181], v[80:83]
	v_mfma_f32_16x16x32_bf16 v[68:71], v[206:209], v[186:189], v[68:71]
	v_mfma_f32_16x16x32_bf16 v[64:67], v[214:217], v[186:189], v[64:67]
	v_mfma_f32_16x16x32_bf16 v[116:119], v[210:213], v[166:169], v[116:119]
	v_mfma_f32_16x16x32_bf16 v[112:115], v[218:221], v[166:169], v[112:115]
	v_mfma_f32_16x16x32_bf16 v[100:103], v[210:213], v[174:177], v[100:103]
	v_mfma_f32_16x16x32_bf16 v[96:99], v[218:221], v[174:177], v[96:99]
	v_mfma_f32_16x16x32_bf16 v[84:87], v[210:213], v[182:185], v[84:87]
	v_mfma_f32_16x16x32_bf16 v[80:83], v[218:221], v[182:185], v[80:83]
	v_mfma_f32_16x16x32_bf16 v[68:71], v[210:213], v[202:205], v[68:71]
	v_mfma_f32_16x16x32_bf16 v[64:67], v[218:221], v[202:205], v[64:67]
	s_mov_b32 m0, s29
	s_barrier
	ds_read_b128 v[162:165], v148 offset:49152
	ds_read_b128 v[166:169], v148 offset:50176
	ds_read_b128 v[170:173], v148 offset:51200
	ds_read_b128 v[174:177], v148 offset:52224
	ds_read_b128 v[178:181], v148 offset:53248
	ds_read_b128 v[182:185], v148 offset:54272
	ds_read_b128 v[186:189], v148 offset:55296
	global_load_lds_dwordx4 v128, s[82:83]
	s_mov_b32 m0, s30
	ds_read_b128 v[202:205], v148 offset:56320
	global_load_lds_dwordx4 v130, s[82:83]
	s_barrier
	s_waitcnt lgkmcnt(0)
	v_mfma_f32_16x16x32_bf16 v[60:63], v[138:141], v[162:165], v[60:63]
	v_mfma_f32_16x16x32_bf16 v[56:59], v[154:157], v[162:165], v[56:59]
	v_mfma_f32_16x16x32_bf16 v[44:47], v[138:141], v[170:173], v[44:47]
	v_mfma_f32_16x16x32_bf16 v[40:43], v[154:157], v[170:173], v[40:43]
	v_mfma_f32_16x16x32_bf16 v[28:31], v[138:141], v[178:181], v[28:31]
	v_mfma_f32_16x16x32_bf16 v[24:27], v[154:157], v[178:181], v[24:27]
	v_mfma_f32_16x16x32_bf16 v[12:15], v[138:141], v[186:189], v[12:15]
	v_mfma_f32_16x16x32_bf16 v[8:11], v[154:157], v[186:189], v[8:11]
	v_mfma_f32_16x16x32_bf16 v[60:63], v[150:153], v[166:169], v[60:63]
	v_mfma_f32_16x16x32_bf16 v[56:59], v[158:161], v[166:169], v[56:59]
	v_mfma_f32_16x16x32_bf16 v[44:47], v[150:153], v[174:177], v[44:47]
	v_mfma_f32_16x16x32_bf16 v[40:43], v[158:161], v[174:177], v[40:43]
	v_mfma_f32_16x16x32_bf16 v[28:31], v[150:153], v[182:185], v[28:31]
	v_mfma_f32_16x16x32_bf16 v[24:27], v[158:161], v[182:185], v[24:27]
	v_mfma_f32_16x16x32_bf16 v[12:15], v[150:153], v[202:205], v[12:15]
	v_mfma_f32_16x16x32_bf16 v[8:11], v[158:161], v[202:205], v[8:11]
	s_barrier
	s_mov_b32 m0, s89
	s_nop 0
	global_load_lds_dwordx4 v194, s[84:85]
	s_add_i32 m0, s89, 0x2000
	s_nop 0
	global_load_lds_dwordx4 v132, s[84:85]
	s_waitcnt vmcnt(6)
	s_barrier
	v_mfma_f32_16x16x32_bf16 v[52:55], v[206:209], v[162:165], v[52:55]
	v_mfma_f32_16x16x32_bf16 v[48:51], v[214:217], v[162:165], v[48:51]
	v_mfma_f32_16x16x32_bf16 v[36:39], v[206:209], v[170:173], v[36:39]
	v_mfma_f32_16x16x32_bf16 v[32:35], v[214:217], v[170:173], v[32:35]
	v_mfma_f32_16x16x32_bf16 v[20:23], v[206:209], v[178:181], v[20:23]
	v_mfma_f32_16x16x32_bf16 v[16:19], v[214:217], v[178:181], v[16:19]
	v_mfma_f32_16x16x32_bf16 v[4:7], v[206:209], v[186:189], v[4:7]
	v_mfma_f32_16x16x32_bf16 v[0:3], v[214:217], v[186:189], v[0:3]
	v_mfma_f32_16x16x32_bf16 v[52:55], v[210:213], v[166:169], v[52:55]
	v_mfma_f32_16x16x32_bf16 v[48:51], v[218:221], v[166:169], v[48:51]
	v_mfma_f32_16x16x32_bf16 v[36:39], v[210:213], v[174:177], v[36:39]
	v_mfma_f32_16x16x32_bf16 v[32:35], v[218:221], v[174:177], v[32:35]
	v_mfma_f32_16x16x32_bf16 v[20:23], v[210:213], v[182:185], v[20:23]
	v_mfma_f32_16x16x32_bf16 v[16:19], v[218:221], v[182:185], v[16:19]
	v_mfma_f32_16x16x32_bf16 v[4:7], v[210:213], v[202:205], v[4:7]
	v_mfma_f32_16x16x32_bf16 v[0:3], v[218:221], v[202:205], v[0:3]
	s_add_u32 s40, s40, 0x100
	s_addc_u32 s41, s41, 0
	s_add_u32 s16, s16, 0x100
	s_addc_u32 s17, s17, 0
	s_cmp_ge_i32 s42, s31
	s_mov_b32 s18, s42
	s_barrier
	s_cbranch_scc0 .LBB0_528
